# K-loops: last iteration without the 14 dummy next-tile prefetch DMAs when the block has no next tile
# baseline (speedup 1.0000x reference)
; #define PG8_STAGE(bufoff, gbase, voff) do { _Pragma("unroll") for (int _i = 0; _i < 2; ++_i) \
;         __builtin_amdgcn_global_load_lds((const unsigned*)((const char*)(gbase) + (voff)[_i]), (PG8_LAS unsigned*)(lds + (bufoff) + ldsw + _i * 8192), 16, 0, 0); } while (0)
; #define PG8_LDA(dst, b, h) do { _Pragma("unroll") for (int m = 0; m < 4; ++m) _Pragma("unroll") for (int k = 0; k < 2; ++k) dst[m][k] = *(const PG8_LAS bf16x8*)(lds + PG8_SA(b, h) + aoff + m * 2048 + k * 1024); } while (0)
; #define PG8_LDB(dst, b, h) do { _Pragma("unroll") for (int n = 0; n < 2; ++n) _Pragma("unroll") for (int k = 0; k < 2; ++k) dst[n][k] = *(const PG8_LAS bf16x8*)(lds + PG8_SB(b, h) + boff + n * 2048 + k * 1024); } while (0)
; #define PG8_MMA(ai, bj, At, Bt) do { __builtin_amdgcn_s_setprio(1); _Pragma("unroll") for (int m = 0; m < 4; ++m) _Pragma("unroll") for (int n = 0; n < 2; ++n) _Pragma("unroll") for (int k = 0; k < 2; ++k) \
;         acc[ai][bj][m][n] = __builtin_amdgcn_mfma_f32_16x16x32_bf16(Bt[n][k], At[m][k], acc[ai][bj][m][n], 0, 0, 0); __builtin_amdgcn_s_setprio(0); } while (0)
; #define PG8_WAIT_V(n) asm volatile("s_waitcnt vmcnt(" #n ")" ::: "memory")
; template <class Epi, class Sched, bool ALIGN_EPI = false, bool SP2 = false>
; __device__ __forceinline__ void gemm_phase(PG8_LAS unsigned char* lds, const Gemm g, const Sched& S, const Epi& E) {
;     ...
;             PG8_LDB(B0, 0, 0); PG8_LDB(B1, 0, 1); PG8_SCHED; PG8_LDA(At, 0, 0); PG8_STAGE(PG8_SA(1, 1), a1 + hstep, voffA);
;             PG8_WAIT_V(8); PG8_WAIT_L(0); PG8_BAR; PG8_MMA(0, 0, At, B0); PG8_MMA(0, 1, At, B1); PG8_BAR; PG8_SCHED;
;             PG8_LDA(At, 0, 1); PG8_STAGE(PG8_SB(0, 0), b2, voffB); PG8_STAGE(PG8_SB(0, 1), b2 + hstep, voffB); PG8_STAGE(PG8_SA(0, 0), a2, voffA);
;             PG8_WAIT_V(8); PG8_WAIT_L(0); PG8_BAR; PG8_MMA(1, 0, At, B0); PG8_MMA(1, 1, At, B1); PG8_BAR; PG8_SCHED;
;             PG8_LDB(B0, 1, 0); PG8_LDB(B1, 1, 1); PG8_SCHED; PG8_LDA(At, 1, 0); PG8_STAGE(PG8_SA(0, 1), a2 + hstep, voffA);
;             PG8_WAIT_V(8); PG8_WAIT_L(0); PG8_BAR; PG8_MMA(0, 0, At, B0); PG8_MMA(0, 1, At, B1); PG8_BAR; PG8_SCHED;
;             PG8_LDA(At, 1, 1); PG8_STAGE(PG8_SB(1, 0), b3, voffB); PG8_STAGE(PG8_SB(1, 1), b3 + hstep, voffB); PG8_STAGE(PG8_SA(1, 0), a3, voffA);
;             PG8_WAIT_V(8); PG8_WAIT_L(0); PG8_BAR; PG8_MMA(1, 0, At, B0); PG8_MMA(1, 1, At, B1); PG8_BAR; PG8_SCHED;
.Lnl_110_7:
	s_barrier
	s_waitcnt lgkmcnt(0)
	v_mfma_f32_16x16x32_bf16 v[94:97], v[146:149], v[186:189], v[94:97]
	v_mfma_f32_16x16x32_bf16 v[90:93], v[154:157], v[186:189], v[90:93]
	v_mfma_f32_16x16x32_bf16 v[86:89], v[146:149], v[194:197], v[86:89]
	v_mfma_f32_16x16x32_bf16 v[82:85], v[154:157], v[194:197], v[82:85]
	v_mfma_f32_16x16x32_bf16 v[78:81], v[146:149], v[202:205], v[78:81]
	v_mfma_f32_16x16x32_bf16 v[74:77], v[154:157], v[202:205], v[74:77]
	v_mfma_f32_16x16x32_bf16 v[70:73], v[146:149], v[212:215], v[70:73]
	v_mfma_f32_16x16x32_bf16 v[66:69], v[154:157], v[212:215], v[66:69]
	v_mfma_f32_16x16x32_bf16 v[94:97], v[150:153], v[190:193], v[94:97]
	v_mfma_f32_16x16x32_bf16 v[90:93], v[166:169], v[190:193], v[90:93]
	v_mfma_f32_16x16x32_bf16 v[86:89], v[150:153], v[198:201], v[86:89]
	v_mfma_f32_16x16x32_bf16 v[82:85], v[166:169], v[198:201], v[82:85]
	v_mfma_f32_16x16x32_bf16 v[78:81], v[150:153], v[208:211], v[78:81]
	v_mfma_f32_16x16x32_bf16 v[74:77], v[166:169], v[208:211], v[74:77]
	v_mfma_f32_16x16x32_bf16 v[70:73], v[150:153], v[216:219], v[70:73]
	v_mfma_f32_16x16x32_bf16 v[66:69], v[166:169], v[216:219], v[66:69]
	v_mfma_f32_16x16x32_bf16 v[30:33], v[170:173], v[186:189], v[30:33]
	v_mfma_f32_16x16x32_bf16 v[26:29], v[178:181], v[186:189], v[26:29]
	v_mfma_f32_16x16x32_bf16 v[22:25], v[170:173], v[194:197], v[22:25]
	v_mfma_f32_16x16x32_bf16 v[18:21], v[178:181], v[194:197], v[18:21]
	v_mfma_f32_16x16x32_bf16 v[14:17], v[170:173], v[202:205], v[14:17]
	v_mfma_f32_16x16x32_bf16 v[10:13], v[178:181], v[202:205], v[10:13]
	v_mfma_f32_16x16x32_bf16 v[6:9], v[170:173], v[212:215], v[6:9]
	v_mfma_f32_16x16x32_bf16 v[2:5], v[178:181], v[212:215], v[2:5]
	v_mfma_f32_16x16x32_bf16 v[30:33], v[174:177], v[190:193], v[30:33]
	v_mfma_f32_16x16x32_bf16 v[26:29], v[182:185], v[190:193], v[26:29]
	v_mfma_f32_16x16x32_bf16 v[22:25], v[174:177], v[198:201], v[22:25]
	v_mfma_f32_16x16x32_bf16 v[18:21], v[182:185], v[198:201], v[18:21]
	v_mfma_f32_16x16x32_bf16 v[14:17], v[174:177], v[208:211], v[14:17]
	v_mfma_f32_16x16x32_bf16 v[10:13], v[182:185], v[208:211], v[10:13]
	v_mfma_f32_16x16x32_bf16 v[6:9], v[174:177], v[216:219], v[6:9]
	v_mfma_f32_16x16x32_bf16 v[2:5], v[182:185], v[216:219], v[2:5]
	s_add_i32 s84, s84, 2
	s_add_u32 s6, s6, 0x100
	s_addc_u32 s7, s7, 0
	s_add_u32 s73, s73, 0x100
	s_addc_u32 s75, s75, 0
	s_cmp_gt_u32 s84, 11
	s_barrier
	s_cbranch_scc0 .LBB0_110
	s_cmp_gt_u32 s84, 13
	s_cbranch_scc1 .Ltl_110_done
	s_cmp_lg_u64 s[4:5], 0
	s_cbranch_scc1 .LBB0_110
	ds_read_b128 v[146:149], v160
	ds_read_b128 v[150:153], v160 offset:1024
	ds_read_b128 v[154:157], v160 offset:2048
	ds_read_b128 v[166:169], v160 offset:3072
	ds_read_b128 v[170:173], v161
	ds_read_b128 v[174:177], v161 offset:1024
	ds_read_b128 v[178:181], v161 offset:2048
	ds_read_b128 v[182:185], v161 offset:3072
	s_add_u32 s8, s6, 0xfffc0080
	s_addc_u32 s9, s7, -1
	s_cmp_eq_u32 s84, 12
	s_cselect_b32 s83, s1, s9
	s_cselect_b32 s82, s33, s8
	s_cselect_b32 s9, s60, s75
	s_cselect_b32 s8, s61, s73
	v_lshl_add_u64 v[220:221], s[6:7], 0, v[138:139]
	s_add_i32 m0, s81, 0xc000
	ds_read_b128 v[186:189], v162
	ds_read_b128 v[190:193], v162 offset:1024
	ds_read_b128 v[194:197], v162 offset:2048
	ds_read_b128 v[198:201], v162 offset:3072
	ds_read_b128 v[202:205], v162 offset:4096
	ds_read_b128 v[208:211], v162 offset:5120
	ds_read_b128 v[212:215], v162 offset:6144
	ds_read_b128 v[216:219], v162 offset:7168
	global_load_lds_dwordx4 v[220:221], off
	v_lshl_add_u64 v[220:221], s[6:7], 0, v[140:141]
	s_add_i32 m0, s81, 0xe000
	s_nop 0
	global_load_lds_dwordx4 v[220:221], off
	s_waitcnt vmcnt(8)
	s_bitcmp1_b32 s68, 0
	s_cbranch_scc1 .Lnlt_110_4
	s_waitcnt lgkmcnt(0)
.Lnlt_110_4:
	s_barrier
	s_waitcnt lgkmcnt(0)
	v_mfma_f32_16x16x32_bf16 v[126:129], v[146:149], v[186:189], v[126:129]
	v_mfma_f32_16x16x32_bf16 v[122:125], v[154:157], v[186:189], v[122:125]
	v_mfma_f32_16x16x32_bf16 v[118:121], v[146:149], v[194:197], v[118:121]
	v_mfma_f32_16x16x32_bf16 v[114:117], v[154:157], v[194:197], v[114:117]
	v_mfma_f32_16x16x32_bf16 v[110:113], v[146:149], v[202:205], v[110:113]
	v_mfma_f32_16x16x32_bf16 v[106:109], v[154:157], v[202:205], v[106:109]
	v_mfma_f32_16x16x32_bf16 v[102:105], v[146:149], v[212:215], v[102:105]
	v_mfma_f32_16x16x32_bf16 v[98:101], v[154:157], v[212:215], v[98:101]
	v_mfma_f32_16x16x32_bf16 v[126:129], v[150:153], v[190:193], v[126:129]
	v_mfma_f32_16x16x32_bf16 v[122:125], v[166:169], v[190:193], v[122:125]
	v_mfma_f32_16x16x32_bf16 v[118:121], v[150:153], v[198:201], v[118:121]
	v_mfma_f32_16x16x32_bf16 v[114:117], v[166:169], v[198:201], v[114:117]
	v_mfma_f32_16x16x32_bf16 v[110:113], v[150:153], v[208:211], v[110:113]
	v_mfma_f32_16x16x32_bf16 v[106:109], v[166:169], v[208:211], v[106:109]
	v_mfma_f32_16x16x32_bf16 v[102:105], v[150:153], v[216:219], v[102:105]
	v_mfma_f32_16x16x32_bf16 v[98:101], v[166:169], v[216:219], v[98:101]
	v_mfma_f32_16x16x32_bf16 v[62:65], v[170:173], v[186:189], v[62:65]
	v_mfma_f32_16x16x32_bf16 v[58:61], v[178:181], v[186:189], v[58:61]
	v_mfma_f32_16x16x32_bf16 v[54:57], v[170:173], v[194:197], v[54:57]
	v_mfma_f32_16x16x32_bf16 v[50:53], v[178:181], v[194:197], v[50:53]
	v_mfma_f32_16x16x32_bf16 v[46:49], v[170:173], v[202:205], v[46:49]
	v_mfma_f32_16x16x32_bf16 v[42:45], v[178:181], v[202:205], v[42:45]
	v_mfma_f32_16x16x32_bf16 v[38:41], v[170:173], v[212:215], v[38:41]
	v_mfma_f32_16x16x32_bf16 v[34:37], v[178:181], v[212:215], v[34:37]
	v_mfma_f32_16x16x32_bf16 v[62:65], v[174:177], v[190:193], v[62:65]
	v_mfma_f32_16x16x32_bf16 v[58:61], v[182:185], v[190:193], v[58:61]
	v_mfma_f32_16x16x32_bf16 v[54:57], v[174:177], v[198:201], v[54:57]
	v_mfma_f32_16x16x32_bf16 v[50:53], v[182:185], v[198:201], v[50:53]
	v_mfma_f32_16x16x32_bf16 v[46:49], v[174:177], v[208:211], v[46:49]
	v_mfma_f32_16x16x32_bf16 v[42:45], v[182:185], v[208:211], v[42:45]
	v_mfma_f32_16x16x32_bf16 v[38:41], v[174:177], v[216:219], v[38:41]
	v_mfma_f32_16x16x32_bf16 v[34:37], v[182:185], v[216:219], v[34:37]
	s_barrier
	s_add_i32 s85, s30, s87
	s_mov_b32 m0, s85
	ds_read_b128 v[186:189], v162 offset:16384
	ds_read_b128 v[190:193], v162 offset:17408
	ds_read_b128 v[194:197], v162 offset:18432
	ds_read_b128 v[198:201], v162 offset:19456
	ds_read_b128 v[202:205], v162 offset:20480
	ds_read_b128 v[208:211], v162 offset:21504
	ds_read_b128 v[212:215], v162 offset:22528
	ds_read_b128 v[216:219], v162 offset:23552
	s_add_i32 m0, s85, 0x2000
	s_add_u32 vcc_lo, s8, 0x40000
	v_lshl_add_u64 v[222:223], s[8:9], 0, v[136:137]
	s_addc_u32 vcc_hi, s9, 0
	s_add_i32 s85, s31, s87
	s_mov_b32 m0, s85
	v_lshl_add_u64 v[226:227], s[82:83], 0, v[134:135]
	s_add_i32 m0, s85, 0x2000
	s_nop 0
	v_lshl_add_u64 v[224:225], s[82:83], 0, v[130:131]
	s_mov_b32 m0, s81
	s_nop 0
	s_mov_b32 m0, s88
	s_nop 0
	s_waitcnt vmcnt(2)
	s_bitcmp1_b32 s68, 0
	s_cbranch_scc1 .Lnlt_110_5
	s_waitcnt lgkmcnt(0)
; #define PG8_STAGE(bufoff, gbase, voff) do { _Pragma("unroll") for (int _i = 0; _i < 2; ++_i) \
;         __builtin_amdgcn_global_load_lds((const unsigned*)((const char*)(gbase) + (voff)[_i]), (PG8_LAS unsigned*)(lds + (bufoff) + ldsw + _i * 8192), 16, 0, 0); } while (0)
; #define PG8_LDA(dst, b, h) do { _Pragma("unroll") for (int m = 0; m < 4; ++m) _Pragma("unroll") for (int k = 0; k < 2; ++k) dst[m][k] = *(const PG8_LAS bf16x8*)(lds + PG8_SA(b, h) + aoff + m * 2048 + k * 1024); } while (0)
; #define PG8_LDB(dst, b, h) do { _Pragma("unroll") for (int n = 0; n < 2; ++n) _Pragma("unroll") for (int k = 0; k < 2; ++k) dst[n][k] = *(const PG8_LAS bf16x8*)(lds + PG8_SB(b, h) + boff + n * 2048 + k * 1024); } while (0)
; #define PG8_MMA(ai, bj, At, Bt) do { __builtin_amdgcn_s_setprio(1); _Pragma("unroll") for (int m = 0; m < 4; ++m) _Pragma("unroll") for (int n = 0; n < 2; ++n) _Pragma("unroll") for (int k = 0; k < 2; ++k) \
;         acc[ai][bj][m][n] = __builtin_amdgcn_mfma_f32_16x16x32_bf16(Bt[n][k], At[m][k], acc[ai][bj][m][n], 0, 0, 0); __builtin_amdgcn_s_setprio(0); } while (0)
; #define PG8_WAIT_V(n) asm volatile("s_waitcnt vmcnt(" #n ")" ::: "memory")
; template <class Epi, class Sched, bool ALIGN_EPI = false, bool SP2 = false>
; __device__ __forceinline__ void gemm_phase(PG8_LAS unsigned char* lds, const Gemm g, const Sched& S, const Epi& E) {
;     ...
;             PG8_LDB(B0, 0, 0); PG8_LDB(B1, 0, 1); PG8_SCHED; PG8_LDA(At, 0, 0); PG8_STAGE(PG8_SA(1, 1), a1 + hstep, voffA);
;             PG8_WAIT_V(8); PG8_WAIT_L(0); PG8_BAR; PG8_MMA(0, 0, At, B0); PG8_MMA(0, 1, At, B1); PG8_BAR; PG8_SCHED;
;             PG8_LDA(At, 0, 1); PG8_STAGE(PG8_SB(0, 0), b2, voffB); PG8_STAGE(PG8_SB(0, 1), b2 + hstep, voffB); PG8_STAGE(PG8_SA(0, 0), a2, voffA);
;             PG8_WAIT_V(8); PG8_WAIT_L(0); PG8_BAR; PG8_MMA(1, 0, At, B0); PG8_MMA(1, 1, At, B1); PG8_BAR; PG8_SCHED;
;             PG8_LDB(B0, 1, 0); PG8_LDB(B1, 1, 1); PG8_SCHED; PG8_LDA(At, 1, 0); PG8_STAGE(PG8_SA(0, 1), a2 + hstep, voffA);
;             PG8_WAIT_V(8); PG8_WAIT_L(0); PG8_BAR; PG8_MMA(0, 0, At, B0); PG8_MMA(0, 1, At, B1); PG8_BAR; PG8_SCHED;
;             PG8_LDA(At, 1, 1); PG8_STAGE(PG8_SB(1, 0), b3, voffB); PG8_STAGE(PG8_SB(1, 1), b3 + hstep, voffB); PG8_STAGE(PG8_SA(1, 0), a3, voffA);
;             PG8_WAIT_V(8); PG8_WAIT_L(0); PG8_BAR; PG8_MMA(1, 0, At, B0); PG8_MMA(1, 1, At, B1); PG8_BAR; PG8_SCHED;
.Lnlt_110_5:
	s_barrier
	s_waitcnt lgkmcnt(0)
	v_mfma_f32_16x16x32_bf16 v[94:97], v[146:149], v[186:189], v[94:97]
	v_mfma_f32_16x16x32_bf16 v[90:93], v[154:157], v[186:189], v[90:93]
	v_mfma_f32_16x16x32_bf16 v[86:89], v[146:149], v[194:197], v[86:89]
	v_mfma_f32_16x16x32_bf16 v[82:85], v[154:157], v[194:197], v[82:85]
	v_mfma_f32_16x16x32_bf16 v[78:81], v[146:149], v[202:205], v[78:81]
	v_mfma_f32_16x16x32_bf16 v[74:77], v[154:157], v[202:205], v[74:77]
	v_mfma_f32_16x16x32_bf16 v[70:73], v[146:149], v[212:215], v[70:73]
	v_mfma_f32_16x16x32_bf16 v[66:69], v[154:157], v[212:215], v[66:69]
	v_mfma_f32_16x16x32_bf16 v[94:97], v[150:153], v[190:193], v[94:97]
	v_mfma_f32_16x16x32_bf16 v[90:93], v[166:169], v[190:193], v[90:93]
	v_mfma_f32_16x16x32_bf16 v[86:89], v[150:153], v[198:201], v[86:89]
	v_mfma_f32_16x16x32_bf16 v[82:85], v[166:169], v[198:201], v[82:85]
	v_mfma_f32_16x16x32_bf16 v[78:81], v[150:153], v[208:211], v[78:81]
	v_mfma_f32_16x16x32_bf16 v[74:77], v[166:169], v[208:211], v[74:77]
	v_mfma_f32_16x16x32_bf16 v[70:73], v[150:153], v[216:219], v[70:73]
	v_mfma_f32_16x16x32_bf16 v[66:69], v[166:169], v[216:219], v[66:69]
	v_mfma_f32_16x16x32_bf16 v[30:33], v[170:173], v[186:189], v[30:33]
	v_mfma_f32_16x16x32_bf16 v[26:29], v[178:181], v[186:189], v[26:29]
	v_mfma_f32_16x16x32_bf16 v[22:25], v[170:173], v[194:197], v[22:25]
	v_mfma_f32_16x16x32_bf16 v[18:21], v[178:181], v[194:197], v[18:21]
	v_mfma_f32_16x16x32_bf16 v[14:17], v[170:173], v[202:205], v[14:17]
	v_mfma_f32_16x16x32_bf16 v[10:13], v[178:181], v[202:205], v[10:13]
	v_mfma_f32_16x16x32_bf16 v[6:9], v[170:173], v[212:215], v[6:9]
	v_mfma_f32_16x16x32_bf16 v[2:5], v[178:181], v[212:215], v[2:5]
	v_mfma_f32_16x16x32_bf16 v[30:33], v[174:177], v[190:193], v[30:33]
	v_mfma_f32_16x16x32_bf16 v[26:29], v[182:185], v[190:193], v[26:29]
	v_mfma_f32_16x16x32_bf16 v[22:25], v[174:177], v[198:201], v[22:25]
	v_mfma_f32_16x16x32_bf16 v[18:21], v[182:185], v[198:201], v[18:21]
	v_mfma_f32_16x16x32_bf16 v[14:17], v[174:177], v[208:211], v[14:17]
	v_mfma_f32_16x16x32_bf16 v[10:13], v[182:185], v[208:211], v[10:13]
	v_mfma_f32_16x16x32_bf16 v[6:9], v[174:177], v[216:219], v[6:9]
	v_mfma_f32_16x16x32_bf16 v[2:5], v[182:185], v[216:219], v[2:5]
	s_barrier
	s_add_i32 s85, 0, 0x18000
	v_add_u32_e32 v165, s85, v158
	s_add_i32 vcc_lo, 0, 0x1c000
	ds_read_b128 v[146:149], v165
	ds_read_b128 v[150:153], v165 offset:1024
	ds_read_b128 v[154:157], v165 offset:2048
	ds_read_b128 v[166:169], v165 offset:3072
	v_add_u32_e32 v165, vcc_lo, v158
	ds_read_b128 v[170:173], v165
	ds_read_b128 v[174:177], v165 offset:1024
	ds_read_b128 v[178:181], v165 offset:2048
	ds_read_b128 v[182:185], v165 offset:3072
	s_add_u32 s82, s82, 0x40000
	s_addc_u32 s83, s83, 0
	s_mov_b32 m0, s89
	ds_read_b128 v[186:189], v162 offset:32768
	ds_read_b128 v[190:193], v162 offset:33792
	ds_read_b128 v[194:197], v162 offset:34816
	ds_read_b128 v[198:201], v162 offset:35840
	ds_read_b128 v[202:205], v162 offset:36864
	ds_read_b128 v[208:211], v162 offset:37888
	ds_read_b128 v[212:215], v162 offset:38912
	ds_read_b128 v[216:219], v162 offset:39936
	s_mov_b32 m0, s90
	s_nop 0
	s_waitcnt vmcnt(0)
	s_bitcmp1_b32 s68, 0
	s_cbranch_scc1 .Lnlt_110_6
	s_waitcnt lgkmcnt(0)
; #define PG8_STAGE(bufoff, gbase, voff) do { _Pragma("unroll") for (int _i = 0; _i < 2; ++_i) \
;         __builtin_amdgcn_global_load_lds((const unsigned*)((const char*)(gbase) + (voff)[_i]), (PG8_LAS unsigned*)(lds + (bufoff) + ldsw + _i * 8192), 16, 0, 0); } while (0)
; #define PG8_LDA(dst, b, h) do { _Pragma("unroll") for (int m = 0; m < 4; ++m) _Pragma("unroll") for (int k = 0; k < 2; ++k) dst[m][k] = *(const PG8_LAS bf16x8*)(lds + PG8_SA(b, h) + aoff + m * 2048 + k * 1024); } while (0)
; #define PG8_MMA(ai, bj, At, Bt) do { __builtin_amdgcn_s_setprio(1); _Pragma("unroll") for (int m = 0; m < 4; ++m) _Pragma("unroll") for (int n = 0; n < 2; ++n) _Pragma("unroll") for (int k = 0; k < 2; ++k) \
;         acc[ai][bj][m][n] = __builtin_amdgcn_mfma_f32_16x16x32_bf16(Bt[n][k], At[m][k], acc[ai][bj][m][n], 0, 0, 0); __builtin_amdgcn_s_setprio(0); } while (0)
; #define PG8_WAIT_V(n) asm volatile("s_waitcnt vmcnt(" #n ")" ::: "memory")
; #define PG8_WAIT_L(n) asm volatile("s_waitcnt lgkmcnt(" #n ")" ::: "memory")
; #define PG8_BAR __builtin_amdgcn_s_barrier()
; #define PG8_SCHED __builtin_amdgcn_sched_barrier(0)
; template <class Epi, class Sched, bool ALIGN_EPI = false, bool SP2 = false>
; __device__ __forceinline__ void gemm_phase(PG8_LAS unsigned char* lds, const Gemm g, const Sched& S, const Epi& E) {
;     ...
;             PG8_WAIT_V(8); PG8_WAIT_L(0); PG8_BAR; PG8_MMA(0, 0, At, B0); PG8_MMA(0, 1, At, B1); PG8_BAR; PG8_SCHED;
;             PG8_LDA(At, 1, 1); PG8_STAGE(PG8_SB(1, 0), b3, voffB); PG8_STAGE(PG8_SB(1, 1), b3 + hstep, voffB); PG8_STAGE(PG8_SA(1, 0), a3, voffA);
;             PG8_WAIT_V(8); PG8_WAIT_L(0); PG8_BAR; PG8_MMA(1, 0, At, B0); PG8_MMA(1, 1, At, B1); PG8_BAR; PG8_SCHED;
.Lnlt_110_6:
	s_barrier
	s_waitcnt lgkmcnt(0)
	v_mfma_f32_16x16x32_bf16 v[126:129], v[146:149], v[186:189], v[126:129]
	v_mfma_f32_16x16x32_bf16 v[122:125], v[154:157], v[186:189], v[122:125]
	v_mfma_f32_16x16x32_bf16 v[118:121], v[146:149], v[194:197], v[118:121]
	v_mfma_f32_16x16x32_bf16 v[114:117], v[154:157], v[194:197], v[114:117]
	v_mfma_f32_16x16x32_bf16 v[110:113], v[146:149], v[202:205], v[110:113]
	v_mfma_f32_16x16x32_bf16 v[106:109], v[154:157], v[202:205], v[106:109]
	v_mfma_f32_16x16x32_bf16 v[102:105], v[146:149], v[212:215], v[102:105]
	v_mfma_f32_16x16x32_bf16 v[98:101], v[154:157], v[212:215], v[98:101]
	v_mfma_f32_16x16x32_bf16 v[126:129], v[150:153], v[190:193], v[126:129]
	v_mfma_f32_16x16x32_bf16 v[122:125], v[166:169], v[190:193], v[122:125]
	v_mfma_f32_16x16x32_bf16 v[118:121], v[150:153], v[198:201], v[118:121]
	v_mfma_f32_16x16x32_bf16 v[114:117], v[166:169], v[198:201], v[114:117]
	v_mfma_f32_16x16x32_bf16 v[110:113], v[150:153], v[208:211], v[110:113]
	v_mfma_f32_16x16x32_bf16 v[106:109], v[166:169], v[208:211], v[106:109]
	v_mfma_f32_16x16x32_bf16 v[102:105], v[150:153], v[216:219], v[102:105]
	v_mfma_f32_16x16x32_bf16 v[98:101], v[166:169], v[216:219], v[98:101]
	v_mfma_f32_16x16x32_bf16 v[62:65], v[170:173], v[186:189], v[62:65]
	v_mfma_f32_16x16x32_bf16 v[58:61], v[178:181], v[186:189], v[58:61]
	v_mfma_f32_16x16x32_bf16 v[54:57], v[170:173], v[194:197], v[54:57]
	v_mfma_f32_16x16x32_bf16 v[50:53], v[178:181], v[194:197], v[50:53]
	v_mfma_f32_16x16x32_bf16 v[46:49], v[170:173], v[202:205], v[46:49]
	v_mfma_f32_16x16x32_bf16 v[42:45], v[178:181], v[202:205], v[42:45]
	v_mfma_f32_16x16x32_bf16 v[38:41], v[170:173], v[212:215], v[38:41]
	v_mfma_f32_16x16x32_bf16 v[34:37], v[178:181], v[212:215], v[34:37]
	v_mfma_f32_16x16x32_bf16 v[62:65], v[174:177], v[190:193], v[62:65]
	v_mfma_f32_16x16x32_bf16 v[58:61], v[182:185], v[190:193], v[58:61]
	v_mfma_f32_16x16x32_bf16 v[54:57], v[174:177], v[198:201], v[54:57]
	v_mfma_f32_16x16x32_bf16 v[50:53], v[182:185], v[198:201], v[50:53]
	v_mfma_f32_16x16x32_bf16 v[46:49], v[174:177], v[208:211], v[46:49]
	v_mfma_f32_16x16x32_bf16 v[42:45], v[182:185], v[208:211], v[42:45]
	v_mfma_f32_16x16x32_bf16 v[38:41], v[174:177], v[216:219], v[38:41]
	v_mfma_f32_16x16x32_bf16 v[34:37], v[182:185], v[216:219], v[34:37]
	s_barrier
	s_add_i32 s82, s85, s87
	s_mov_b32 m0, s82
	ds_read_b128 v[186:189], v162 offset:49152
	ds_read_b128 v[190:193], v162 offset:50176
	ds_read_b128 v[194:197], v162 offset:51200
	ds_read_b128 v[198:201], v162 offset:52224
	ds_read_b128 v[202:205], v162 offset:53248
	ds_read_b128 v[208:211], v162 offset:54272
	ds_read_b128 v[212:215], v162 offset:55296
	ds_read_b128 v[216:219], v162 offset:56320
	s_add_u32 s98, s8, s26
	s_addc_u32 s99, s9, s27
	s_add_i32 m0, s82, 0x2000
	s_add_u32 s8, s8, 0x40080
	v_lshl_add_u64 v[220:221], v[222:223], 0, s[26:27]
	s_addc_u32 s9, s9, 0
	s_add_i32 s82, vcc_lo, s87
	s_mov_b32 m0, s82
	s_nop 0
	s_add_i32 m0, s82, 0x2000
	s_nop 0
	v_lshl_add_u64 v[220:221], v[224:225], 0, s[26:27]
	s_mov_b32 m0, s92
	s_nop 0
	v_lshl_add_u64 v[220:221], v[226:227], 0, s[26:27]
	s_mov_b32 m0, s93
	s_nop 0
	s_bitcmp1_b32 s68, 0
	s_cbranch_scc1 .Lnlt_110_7
	s_waitcnt lgkmcnt(0)
.Lnlt_110_7:
	s_barrier
	s_waitcnt lgkmcnt(0)
	v_mfma_f32_16x16x32_bf16 v[94:97], v[146:149], v[186:189], v[94:97]
	v_mfma_f32_16x16x32_bf16 v[90:93], v[154:157], v[186:189], v[90:93]
	v_mfma_f32_16x16x32_bf16 v[86:89], v[146:149], v[194:197], v[86:89]
	v_mfma_f32_16x16x32_bf16 v[82:85], v[154:157], v[194:197], v[82:85]
	v_mfma_f32_16x16x32_bf16 v[78:81], v[146:149], v[202:205], v[78:81]
	v_mfma_f32_16x16x32_bf16 v[74:77], v[154:157], v[202:205], v[74:77]
	v_mfma_f32_16x16x32_bf16 v[70:73], v[146:149], v[212:215], v[70:73]
	v_mfma_f32_16x16x32_bf16 v[66:69], v[154:157], v[212:215], v[66:69]
	v_mfma_f32_16x16x32_bf16 v[94:97], v[150:153], v[190:193], v[94:97]
	v_mfma_f32_16x16x32_bf16 v[90:93], v[166:169], v[190:193], v[90:93]
	v_mfma_f32_16x16x32_bf16 v[86:89], v[150:153], v[198:201], v[86:89]
	v_mfma_f32_16x16x32_bf16 v[82:85], v[166:169], v[198:201], v[82:85]
	v_mfma_f32_16x16x32_bf16 v[78:81], v[150:153], v[208:211], v[78:81]
	v_mfma_f32_16x16x32_bf16 v[74:77], v[166:169], v[208:211], v[74:77]
	v_mfma_f32_16x16x32_bf16 v[70:73], v[150:153], v[216:219], v[70:73]
	v_mfma_f32_16x16x32_bf16 v[66:69], v[166:169], v[216:219], v[66:69]
	v_mfma_f32_16x16x32_bf16 v[30:33], v[170:173], v[186:189], v[30:33]
	v_mfma_f32_16x16x32_bf16 v[26:29], v[178:181], v[186:189], v[26:29]
	v_mfma_f32_16x16x32_bf16 v[22:25], v[170:173], v[194:197], v[22:25]
	v_mfma_f32_16x16x32_bf16 v[18:21], v[178:181], v[194:197], v[18:21]
	v_mfma_f32_16x16x32_bf16 v[14:17], v[170:173], v[202:205], v[14:17]
	v_mfma_f32_16x16x32_bf16 v[10:13], v[178:181], v[202:205], v[10:13]
	v_mfma_f32_16x16x32_bf16 v[6:9], v[170:173], v[212:215], v[6:9]
	v_mfma_f32_16x16x32_bf16 v[2:5], v[178:181], v[212:215], v[2:5]
	v_mfma_f32_16x16x32_bf16 v[30:33], v[174:177], v[190:193], v[30:33]
	v_mfma_f32_16x16x32_bf16 v[26:29], v[182:185], v[190:193], v[26:29]
	v_mfma_f32_16x16x32_bf16 v[22:25], v[174:177], v[198:201], v[22:25]
	v_mfma_f32_16x16x32_bf16 v[18:21], v[182:185], v[198:201], v[18:21]
	v_mfma_f32_16x16x32_bf16 v[14:17], v[174:177], v[208:211], v[14:17]
	v_mfma_f32_16x16x32_bf16 v[10:13], v[182:185], v[208:211], v[10:13]
	v_mfma_f32_16x16x32_bf16 v[6:9], v[174:177], v[216:219], v[6:9]
	v_mfma_f32_16x16x32_bf16 v[2:5], v[182:185], v[216:219], v[2:5]
	s_add_i32 s84, s84, 2
	s_add_u32 s6, s6, 0x100
	s_addc_u32 s7, s7, 0
	s_add_u32 s73, s73, 0x100
	s_addc_u32 s75, s75, 0
	s_barrier
.Ltl_110_done:
	s_mov_b32 s100, 0xbfb8aa3b
	s_mov_b32 s98, 1.0
	s_and_b64 vcc, exec, s[68:69]
	s_cbranch_vccz .LBB0_113
	s_barrier

; #define PG8_STAGE(bufoff, gbase, voff) do { _Pragma("unroll") for (int _i = 0; _i < 2; ++_i) \
;         __builtin_amdgcn_global_load_lds((const unsigned*)((const char*)(gbase) + (voff)[_i]), (PG8_LAS unsigned*)(lds + (bufoff) + ldsw + _i * 8192), 16, 0, 0); } while (0)
; #define PG8_LDA(dst, b, h) do { _Pragma("unroll") for (int m = 0; m < 4; ++m) _Pragma("unroll") for (int k = 0; k < 2; ++k) dst[m][k] = *(const PG8_LAS bf16x8*)(lds + PG8_SA(b, h) + aoff + m * 2048 + k * 1024); } while (0)
; #define PG8_LDB(dst, b, h) do { _Pragma("unroll") for (int n = 0; n < 2; ++n) _Pragma("unroll") for (int k = 0; k < 2; ++k) dst[n][k] = *(const PG8_LAS bf16x8*)(lds + PG8_SB(b, h) + boff + n * 2048 + k * 1024); } while (0)
; #define PG8_MMA(ai, bj, At, Bt) do { __builtin_amdgcn_s_setprio(1); _Pragma("unroll") for (int m = 0; m < 4; ++m) _Pragma("unroll") for (int n = 0; n < 2; ++n) _Pragma("unroll") for (int k = 0; k < 2; ++k) \
;         acc[ai][bj][m][n] = __builtin_amdgcn_mfma_f32_16x16x32_bf16(Bt[n][k], At[m][k], acc[ai][bj][m][n], 0, 0, 0); __builtin_amdgcn_s_setprio(0); } while (0)
; #define PG8_WAIT_V(n) asm volatile("s_waitcnt vmcnt(" #n ")" ::: "memory")
; template <class Epi, class Sched, bool ALIGN_EPI = false, bool SP2 = false>
; __device__ __forceinline__ void gemm_phase(PG8_LAS unsigned char* lds, const Gemm g, const Sched& S, const Epi& E) {
;     ...
;             PG8_LDB(B0, 0, 0); PG8_LDB(B1, 0, 1); PG8_SCHED; PG8_LDA(At, 0, 0); PG8_STAGE(PG8_SA(1, 1), a1 + hstep, voffA);
;             PG8_WAIT_V(8); PG8_WAIT_L(0); PG8_BAR; PG8_MMA(0, 0, At, B0); PG8_MMA(0, 1, At, B1); PG8_BAR; PG8_SCHED;
;             PG8_LDA(At, 0, 1); PG8_STAGE(PG8_SB(0, 0), b2, voffB); PG8_STAGE(PG8_SB(0, 1), b2 + hstep, voffB); PG8_STAGE(PG8_SA(0, 0), a2, voffA);
;             PG8_WAIT_V(8); PG8_WAIT_L(0); PG8_BAR; PG8_MMA(1, 0, At, B0); PG8_MMA(1, 1, At, B1); PG8_BAR; PG8_SCHED;
;             PG8_LDB(B0, 1, 0); PG8_LDB(B1, 1, 1); PG8_SCHED; PG8_LDA(At, 1, 0); PG8_STAGE(PG8_SA(0, 1), a2 + hstep, voffA);
;             PG8_WAIT_V(8); PG8_WAIT_L(0); PG8_BAR; PG8_MMA(0, 0, At, B0); PG8_MMA(0, 1, At, B1); PG8_BAR; PG8_SCHED;
;             PG8_LDA(At, 1, 1); PG8_STAGE(PG8_SB(1, 0), b3, voffB); PG8_STAGE(PG8_SB(1, 1), b3 + hstep, voffB); PG8_STAGE(PG8_SA(1, 0), a3, voffA);
;             PG8_WAIT_V(8); PG8_WAIT_L(0); PG8_BAR; PG8_MMA(1, 0, At, B0); PG8_MMA(1, 1, At, B1); PG8_BAR; PG8_SCHED;
.Lnl_646_7:
	s_barrier
	s_waitcnt lgkmcnt(0)
	v_mfma_f32_16x16x32_bf16 v[62:65], v[148:151], v[184:187], v[62:65]
	v_mfma_f32_16x16x32_bf16 v[58:61], v[160:163], v[184:187], v[58:61]
	v_mfma_f32_16x16x32_bf16 v[46:49], v[148:151], v[192:195], v[46:49]
	v_mfma_f32_16x16x32_bf16 v[42:45], v[160:163], v[192:195], v[42:45]
	v_mfma_f32_16x16x32_bf16 v[30:33], v[148:151], v[200:203], v[30:33]
	v_mfma_f32_16x16x32_bf16 v[26:29], v[160:163], v[200:203], v[26:29]
	v_mfma_f32_16x16x32_bf16 v[14:17], v[148:151], v[212:215], v[14:17]
	v_mfma_f32_16x16x32_bf16 v[10:13], v[160:163], v[212:215], v[10:13]
	v_mfma_f32_16x16x32_bf16 v[62:65], v[156:159], v[188:191], v[62:65]
	v_mfma_f32_16x16x32_bf16 v[58:61], v[164:167], v[188:191], v[58:61]
	v_mfma_f32_16x16x32_bf16 v[46:49], v[156:159], v[196:199], v[46:49]
	v_mfma_f32_16x16x32_bf16 v[42:45], v[164:167], v[196:199], v[42:45]
	v_mfma_f32_16x16x32_bf16 v[30:33], v[156:159], v[208:211], v[30:33]
	v_mfma_f32_16x16x32_bf16 v[26:29], v[164:167], v[208:211], v[26:29]
	v_mfma_f32_16x16x32_bf16 v[14:17], v[156:159], v[216:219], v[14:17]
	v_mfma_f32_16x16x32_bf16 v[10:13], v[164:167], v[216:219], v[10:13]
	v_mfma_f32_16x16x32_bf16 v[54:57], v[168:171], v[184:187], v[54:57]
	v_mfma_f32_16x16x32_bf16 v[50:53], v[176:179], v[184:187], v[50:53]
	v_mfma_f32_16x16x32_bf16 v[38:41], v[168:171], v[192:195], v[38:41]
	v_mfma_f32_16x16x32_bf16 v[34:37], v[176:179], v[192:195], v[34:37]
	v_mfma_f32_16x16x32_bf16 v[22:25], v[168:171], v[200:203], v[22:25]
	v_mfma_f32_16x16x32_bf16 v[18:21], v[176:179], v[200:203], v[18:21]
	v_mfma_f32_16x16x32_bf16 v[6:9], v[168:171], v[212:215], v[6:9]
	v_mfma_f32_16x16x32_bf16 v[2:5], v[176:179], v[212:215], v[2:5]
	v_mfma_f32_16x16x32_bf16 v[54:57], v[172:175], v[188:191], v[54:57]
	v_mfma_f32_16x16x32_bf16 v[50:53], v[180:183], v[188:191], v[50:53]
	v_mfma_f32_16x16x32_bf16 v[38:41], v[172:175], v[196:199], v[38:41]
	v_mfma_f32_16x16x32_bf16 v[34:37], v[180:183], v[196:199], v[34:37]
	v_mfma_f32_16x16x32_bf16 v[22:25], v[172:175], v[208:211], v[22:25]
	v_mfma_f32_16x16x32_bf16 v[18:21], v[180:183], v[208:211], v[18:21]
	v_mfma_f32_16x16x32_bf16 v[6:9], v[172:175], v[216:219], v[6:9]
	v_mfma_f32_16x16x32_bf16 v[2:5], v[180:183], v[216:219], v[2:5]
	s_add_i32 s73, s73, 2
	s_add_u32 s44, s44, 0x100
	s_addc_u32 s45, s45, 0
	s_add_u32 s71, s71, 0x100
	s_addc_u32 s72, s72, 0
	s_cmp_gt_u32 s73, 11
	s_barrier
	s_cbranch_scc0 .LBB0_646
	s_cmp_gt_u32 s73, 13
	s_cbranch_scc1 .Ltl_646_done
	s_cmp_lg_u64 s[6:7], 0
	s_cbranch_scc1 .LBB0_646
	ds_read_b128 v[148:151], v152
	ds_read_b128 v[156:159], v152 offset:1024
	ds_read_b128 v[160:163], v152 offset:2048
	ds_read_b128 v[164:167], v152 offset:3072
	ds_read_b128 v[168:171], v153
	ds_read_b128 v[172:175], v153 offset:1024
	ds_read_b128 v[176:179], v153 offset:2048
	ds_read_b128 v[180:183], v153 offset:3072
	s_add_u32 s46, s44, 0xfffc0080
	s_addc_u32 s47, s45, -1
	s_cmp_eq_u32 s73, 12
	s_cselect_b32 s49, s21, s47
	s_cselect_b32 s48, s27, s46
	s_cselect_b32 s47, s19, s72
	s_cselect_b32 s46, s33, s71
	v_lshl_add_u64 v[204:205], s[44:45], 0, v[140:141]
	s_add_i32 m0, s31, 0xc000
	ds_read_b128 v[184:187], v154
	ds_read_b128 v[188:191], v154 offset:1024
	ds_read_b128 v[192:195], v154 offset:2048
	ds_read_b128 v[196:199], v154 offset:3072
	ds_read_b128 v[200:203], v154 offset:4096
	ds_read_b128 v[208:211], v154 offset:5120
	ds_read_b128 v[212:215], v154 offset:6144
	ds_read_b128 v[216:219], v154 offset:7168
	global_load_lds_dwordx4 v[204:205], off
	v_lshl_add_u64 v[204:205], s[44:45], 0, v[142:143]
	s_add_i32 m0, s31, 0xe000
	s_nop 0
	global_load_lds_dwordx4 v[204:205], off
	s_waitcnt vmcnt(8)
	s_bitcmp1_b32 s16, 0
	s_cbranch_scc1 .Lnlt_646_4
	s_waitcnt lgkmcnt(0)
.Lnlt_646_4:
	s_barrier
	s_waitcnt lgkmcnt(0)
	v_mfma_f32_16x16x32_bf16 v[126:129], v[148:151], v[184:187], v[126:129]
	v_mfma_f32_16x16x32_bf16 v[122:125], v[160:163], v[184:187], v[122:125]
	v_mfma_f32_16x16x32_bf16 v[110:113], v[148:151], v[192:195], v[110:113]
	v_mfma_f32_16x16x32_bf16 v[106:109], v[160:163], v[192:195], v[106:109]
	v_mfma_f32_16x16x32_bf16 v[94:97], v[148:151], v[200:203], v[94:97]
	v_mfma_f32_16x16x32_bf16 v[90:93], v[160:163], v[200:203], v[90:93]
	v_mfma_f32_16x16x32_bf16 v[78:81], v[148:151], v[212:215], v[78:81]
	v_mfma_f32_16x16x32_bf16 v[74:77], v[160:163], v[212:215], v[74:77]
	v_mfma_f32_16x16x32_bf16 v[126:129], v[156:159], v[188:191], v[126:129]
	v_mfma_f32_16x16x32_bf16 v[122:125], v[164:167], v[188:191], v[122:125]
	v_mfma_f32_16x16x32_bf16 v[110:113], v[156:159], v[196:199], v[110:113]
	v_mfma_f32_16x16x32_bf16 v[106:109], v[164:167], v[196:199], v[106:109]
	v_mfma_f32_16x16x32_bf16 v[94:97], v[156:159], v[208:211], v[94:97]
	v_mfma_f32_16x16x32_bf16 v[90:93], v[164:167], v[208:211], v[90:93]
	v_mfma_f32_16x16x32_bf16 v[78:81], v[156:159], v[216:219], v[78:81]
	v_mfma_f32_16x16x32_bf16 v[74:77], v[164:167], v[216:219], v[74:77]
	v_mfma_f32_16x16x32_bf16 v[118:121], v[168:171], v[184:187], v[118:121]
	v_mfma_f32_16x16x32_bf16 v[114:117], v[176:179], v[184:187], v[114:117]
	v_mfma_f32_16x16x32_bf16 v[102:105], v[168:171], v[192:195], v[102:105]
	v_mfma_f32_16x16x32_bf16 v[98:101], v[176:179], v[192:195], v[98:101]
	v_mfma_f32_16x16x32_bf16 v[86:89], v[168:171], v[200:203], v[86:89]
	v_mfma_f32_16x16x32_bf16 v[82:85], v[176:179], v[200:203], v[82:85]
	v_mfma_f32_16x16x32_bf16 v[70:73], v[168:171], v[212:215], v[70:73]
	v_mfma_f32_16x16x32_bf16 v[66:69], v[176:179], v[212:215], v[66:69]
	v_mfma_f32_16x16x32_bf16 v[118:121], v[172:175], v[188:191], v[118:121]
	v_mfma_f32_16x16x32_bf16 v[114:117], v[180:183], v[188:191], v[114:117]
	v_mfma_f32_16x16x32_bf16 v[102:105], v[172:175], v[196:199], v[102:105]
	v_mfma_f32_16x16x32_bf16 v[98:101], v[180:183], v[196:199], v[98:101]
	v_mfma_f32_16x16x32_bf16 v[86:89], v[172:175], v[208:211], v[86:89]
	v_mfma_f32_16x16x32_bf16 v[82:85], v[180:183], v[208:211], v[82:85]
	v_mfma_f32_16x16x32_bf16 v[70:73], v[172:175], v[216:219], v[70:73]
	v_mfma_f32_16x16x32_bf16 v[66:69], v[180:183], v[216:219], v[66:69]
	s_barrier
	s_add_i32 s74, s68, s30
	s_mov_b32 m0, s74
	ds_read_b128 v[184:187], v154 offset:16384
	ds_read_b128 v[188:191], v154 offset:17408
	ds_read_b128 v[192:195], v154 offset:18432
	ds_read_b128 v[196:199], v154 offset:19456
	ds_read_b128 v[200:203], v154 offset:20480
	ds_read_b128 v[208:211], v154 offset:21504
	ds_read_b128 v[212:215], v154 offset:22528
	ds_read_b128 v[216:219], v154 offset:23552
	s_add_i32 m0, s74, 0x2000
	s_add_u32 s74, s46, 0x40000
	v_lshl_add_u64 v[220:221], s[46:47], 0, v[136:137]
	s_addc_u32 s75, s47, 0
	s_add_i32 s76, s69, s30
	s_mov_b32 m0, s76
	v_lshl_add_u64 v[224:225], s[48:49], 0, v[134:135]
	s_add_i32 m0, s76, 0x2000
	s_nop 0
	v_lshl_add_u64 v[222:223], s[48:49], 0, v[130:131]
	s_mov_b32 m0, s31
	s_nop 0
	s_mov_b32 m0, s50
	s_nop 0
	s_waitcnt vmcnt(2)
	s_bitcmp1_b32 s16, 0
	s_cbranch_scc1 .Lnlt_646_5
	s_waitcnt lgkmcnt(0)
; #define PG8_STAGE(bufoff, gbase, voff) do { _Pragma("unroll") for (int _i = 0; _i < 2; ++_i) \
;         __builtin_amdgcn_global_load_lds((const unsigned*)((const char*)(gbase) + (voff)[_i]), (PG8_LAS unsigned*)(lds + (bufoff) + ldsw + _i * 8192), 16, 0, 0); } while (0)
; #define PG8_LDA(dst, b, h) do { _Pragma("unroll") for (int m = 0; m < 4; ++m) _Pragma("unroll") for (int k = 0; k < 2; ++k) dst[m][k] = *(const PG8_LAS bf16x8*)(lds + PG8_SA(b, h) + aoff + m * 2048 + k * 1024); } while (0)
; #define PG8_LDB(dst, b, h) do { _Pragma("unroll") for (int n = 0; n < 2; ++n) _Pragma("unroll") for (int k = 0; k < 2; ++k) dst[n][k] = *(const PG8_LAS bf16x8*)(lds + PG8_SB(b, h) + boff + n * 2048 + k * 1024); } while (0)
; #define PG8_MMA(ai, bj, At, Bt) do { __builtin_amdgcn_s_setprio(1); _Pragma("unroll") for (int m = 0; m < 4; ++m) _Pragma("unroll") for (int n = 0; n < 2; ++n) _Pragma("unroll") for (int k = 0; k < 2; ++k) \
;         acc[ai][bj][m][n] = __builtin_amdgcn_mfma_f32_16x16x32_bf16(Bt[n][k], At[m][k], acc[ai][bj][m][n], 0, 0, 0); __builtin_amdgcn_s_setprio(0); } while (0)
; #define PG8_WAIT_V(n) asm volatile("s_waitcnt vmcnt(" #n ")" ::: "memory")
; template <class Epi, class Sched, bool ALIGN_EPI = false, bool SP2 = false>
; __device__ __forceinline__ void gemm_phase(PG8_LAS unsigned char* lds, const Gemm g, const Sched& S, const Epi& E) {
;     ...
;             PG8_LDB(B0, 0, 0); PG8_LDB(B1, 0, 1); PG8_SCHED; PG8_LDA(At, 0, 0); PG8_STAGE(PG8_SA(1, 1), a1 + hstep, voffA);
;             PG8_WAIT_V(8); PG8_WAIT_L(0); PG8_BAR; PG8_MMA(0, 0, At, B0); PG8_MMA(0, 1, At, B1); PG8_BAR; PG8_SCHED;
;             PG8_LDA(At, 0, 1); PG8_STAGE(PG8_SB(0, 0), b2, voffB); PG8_STAGE(PG8_SB(0, 1), b2 + hstep, voffB); PG8_STAGE(PG8_SA(0, 0), a2, voffA);
;             PG8_WAIT_V(8); PG8_WAIT_L(0); PG8_BAR; PG8_MMA(1, 0, At, B0); PG8_MMA(1, 1, At, B1); PG8_BAR; PG8_SCHED;
;             PG8_LDB(B0, 1, 0); PG8_LDB(B1, 1, 1); PG8_SCHED; PG8_LDA(At, 1, 0); PG8_STAGE(PG8_SA(0, 1), a2 + hstep, voffA);
;             PG8_WAIT_V(8); PG8_WAIT_L(0); PG8_BAR; PG8_MMA(0, 0, At, B0); PG8_MMA(0, 1, At, B1); PG8_BAR; PG8_SCHED;
;             PG8_LDA(At, 1, 1); PG8_STAGE(PG8_SB(1, 0), b3, voffB); PG8_STAGE(PG8_SB(1, 1), b3 + hstep, voffB); PG8_STAGE(PG8_SA(1, 0), a3, voffA);
;             PG8_WAIT_V(8); PG8_WAIT_L(0); PG8_BAR; PG8_MMA(1, 0, At, B0); PG8_MMA(1, 1, At, B1); PG8_BAR; PG8_SCHED;
.Lnlt_646_5:
	s_barrier
	s_waitcnt lgkmcnt(0)
	v_mfma_f32_16x16x32_bf16 v[62:65], v[148:151], v[184:187], v[62:65]
	v_mfma_f32_16x16x32_bf16 v[58:61], v[160:163], v[184:187], v[58:61]
	v_mfma_f32_16x16x32_bf16 v[46:49], v[148:151], v[192:195], v[46:49]
	v_mfma_f32_16x16x32_bf16 v[42:45], v[160:163], v[192:195], v[42:45]
	v_mfma_f32_16x16x32_bf16 v[30:33], v[148:151], v[200:203], v[30:33]
	v_mfma_f32_16x16x32_bf16 v[26:29], v[160:163], v[200:203], v[26:29]
	v_mfma_f32_16x16x32_bf16 v[14:17], v[148:151], v[212:215], v[14:17]
	v_mfma_f32_16x16x32_bf16 v[10:13], v[160:163], v[212:215], v[10:13]
	v_mfma_f32_16x16x32_bf16 v[62:65], v[156:159], v[188:191], v[62:65]
	v_mfma_f32_16x16x32_bf16 v[58:61], v[164:167], v[188:191], v[58:61]
	v_mfma_f32_16x16x32_bf16 v[46:49], v[156:159], v[196:199], v[46:49]
	v_mfma_f32_16x16x32_bf16 v[42:45], v[164:167], v[196:199], v[42:45]
	v_mfma_f32_16x16x32_bf16 v[30:33], v[156:159], v[208:211], v[30:33]
	v_mfma_f32_16x16x32_bf16 v[26:29], v[164:167], v[208:211], v[26:29]
	v_mfma_f32_16x16x32_bf16 v[14:17], v[156:159], v[216:219], v[14:17]
	v_mfma_f32_16x16x32_bf16 v[10:13], v[164:167], v[216:219], v[10:13]
	v_mfma_f32_16x16x32_bf16 v[54:57], v[168:171], v[184:187], v[54:57]
	v_mfma_f32_16x16x32_bf16 v[50:53], v[176:179], v[184:187], v[50:53]
	v_mfma_f32_16x16x32_bf16 v[38:41], v[168:171], v[192:195], v[38:41]
	v_mfma_f32_16x16x32_bf16 v[34:37], v[176:179], v[192:195], v[34:37]
	v_mfma_f32_16x16x32_bf16 v[22:25], v[168:171], v[200:203], v[22:25]
	v_mfma_f32_16x16x32_bf16 v[18:21], v[176:179], v[200:203], v[18:21]
	v_mfma_f32_16x16x32_bf16 v[6:9], v[168:171], v[212:215], v[6:9]
	v_mfma_f32_16x16x32_bf16 v[2:5], v[176:179], v[212:215], v[2:5]
	v_mfma_f32_16x16x32_bf16 v[54:57], v[172:175], v[188:191], v[54:57]
	v_mfma_f32_16x16x32_bf16 v[50:53], v[180:183], v[188:191], v[50:53]
	v_mfma_f32_16x16x32_bf16 v[38:41], v[172:175], v[196:199], v[38:41]
	v_mfma_f32_16x16x32_bf16 v[34:37], v[180:183], v[196:199], v[34:37]
	v_mfma_f32_16x16x32_bf16 v[22:25], v[172:175], v[208:211], v[22:25]
	v_mfma_f32_16x16x32_bf16 v[18:21], v[180:183], v[208:211], v[18:21]
	v_mfma_f32_16x16x32_bf16 v[6:9], v[172:175], v[216:219], v[6:9]
	v_mfma_f32_16x16x32_bf16 v[2:5], v[180:183], v[216:219], v[2:5]
	s_barrier
	s_add_i32 s74, 0, 0x18000
	s_add_i32 s75, 0, 0x1c000
	v_add_u32_e32 v164, s74, v139
	v_add_u32_e32 v180, s75, v139
	ds_read_b128 v[148:151], v164
	ds_read_b128 v[156:159], v164 offset:1024
	ds_read_b128 v[160:163], v164 offset:2048
	ds_read_b128 v[164:167], v164 offset:3072
	ds_read_b128 v[168:171], v180
	ds_read_b128 v[172:175], v180 offset:1024
	ds_read_b128 v[176:179], v180 offset:2048
	ds_read_b128 v[180:183], v180 offset:3072
	s_add_u32 s48, s48, 0x40000
	s_addc_u32 s49, s49, 0
	s_mov_b32 m0, s51
	ds_read_b128 v[184:187], v154 offset:32768
	ds_read_b128 v[188:191], v154 offset:33792
	ds_read_b128 v[192:195], v154 offset:34816
	ds_read_b128 v[196:199], v154 offset:35840
	ds_read_b128 v[200:203], v154 offset:36864
	ds_read_b128 v[208:211], v154 offset:37888
	ds_read_b128 v[212:215], v154 offset:38912
	ds_read_b128 v[216:219], v154 offset:39936
	s_mov_b32 m0, s60
	s_nop 0
	s_waitcnt vmcnt(0)
	s_bitcmp1_b32 s16, 0
	s_cbranch_scc1 .Lnlt_646_6
	s_waitcnt lgkmcnt(0)
; #define PG8_STAGE(bufoff, gbase, voff) do { _Pragma("unroll") for (int _i = 0; _i < 2; ++_i) \
;         __builtin_amdgcn_global_load_lds((const unsigned*)((const char*)(gbase) + (voff)[_i]), (PG8_LAS unsigned*)(lds + (bufoff) + ldsw + _i * 8192), 16, 0, 0); } while (0)
; #define PG8_LDA(dst, b, h) do { _Pragma("unroll") for (int m = 0; m < 4; ++m) _Pragma("unroll") for (int k = 0; k < 2; ++k) dst[m][k] = *(const PG8_LAS bf16x8*)(lds + PG8_SA(b, h) + aoff + m * 2048 + k * 1024); } while (0)
; #define PG8_MMA(ai, bj, At, Bt) do { __builtin_amdgcn_s_setprio(1); _Pragma("unroll") for (int m = 0; m < 4; ++m) _Pragma("unroll") for (int n = 0; n < 2; ++n) _Pragma("unroll") for (int k = 0; k < 2; ++k) \
;         acc[ai][bj][m][n] = __builtin_amdgcn_mfma_f32_16x16x32_bf16(Bt[n][k], At[m][k], acc[ai][bj][m][n], 0, 0, 0); __builtin_amdgcn_s_setprio(0); } while (0)
; #define PG8_WAIT_V(n) asm volatile("s_waitcnt vmcnt(" #n ")" ::: "memory")
; #define PG8_WAIT_L(n) asm volatile("s_waitcnt lgkmcnt(" #n ")" ::: "memory")
; #define PG8_BAR __builtin_amdgcn_s_barrier()
; #define PG8_SCHED __builtin_amdgcn_sched_barrier(0)
; template <class Epi, class Sched, bool ALIGN_EPI = false, bool SP2 = false>
; __device__ __forceinline__ void gemm_phase(PG8_LAS unsigned char* lds, const Gemm g, const Sched& S, const Epi& E) {
;     ...
;             PG8_WAIT_V(8); PG8_WAIT_L(0); PG8_BAR; PG8_MMA(0, 0, At, B0); PG8_MMA(0, 1, At, B1); PG8_BAR; PG8_SCHED;
;             PG8_LDA(At, 1, 1); PG8_STAGE(PG8_SB(1, 0), b3, voffB); PG8_STAGE(PG8_SB(1, 1), b3 + hstep, voffB); PG8_STAGE(PG8_SA(1, 0), a3, voffA);
;             PG8_WAIT_V(8); PG8_WAIT_L(0); PG8_BAR; PG8_MMA(1, 0, At, B0); PG8_MMA(1, 1, At, B1); PG8_BAR; PG8_SCHED;
;     ...
;         if constexpr (ALIGN_EPI) { if (wr == 0) PG8_BAR; }
.Lnlt_646_6:
	s_barrier
	s_waitcnt lgkmcnt(0)
	v_mfma_f32_16x16x32_bf16 v[126:129], v[148:151], v[184:187], v[126:129]
	v_mfma_f32_16x16x32_bf16 v[122:125], v[160:163], v[184:187], v[122:125]
	v_mfma_f32_16x16x32_bf16 v[110:113], v[148:151], v[192:195], v[110:113]
	v_mfma_f32_16x16x32_bf16 v[106:109], v[160:163], v[192:195], v[106:109]
	v_mfma_f32_16x16x32_bf16 v[94:97], v[148:151], v[200:203], v[94:97]
	v_mfma_f32_16x16x32_bf16 v[90:93], v[160:163], v[200:203], v[90:93]
	v_mfma_f32_16x16x32_bf16 v[78:81], v[148:151], v[212:215], v[78:81]
	v_mfma_f32_16x16x32_bf16 v[74:77], v[160:163], v[212:215], v[74:77]
	v_mfma_f32_16x16x32_bf16 v[126:129], v[156:159], v[188:191], v[126:129]
	v_mfma_f32_16x16x32_bf16 v[122:125], v[164:167], v[188:191], v[122:125]
	v_mfma_f32_16x16x32_bf16 v[110:113], v[156:159], v[196:199], v[110:113]
	v_mfma_f32_16x16x32_bf16 v[106:109], v[164:167], v[196:199], v[106:109]
	v_mfma_f32_16x16x32_bf16 v[94:97], v[156:159], v[208:211], v[94:97]
	v_mfma_f32_16x16x32_bf16 v[90:93], v[164:167], v[208:211], v[90:93]
	v_mfma_f32_16x16x32_bf16 v[78:81], v[156:159], v[216:219], v[78:81]
	v_mfma_f32_16x16x32_bf16 v[74:77], v[164:167], v[216:219], v[74:77]
	v_mfma_f32_16x16x32_bf16 v[118:121], v[168:171], v[184:187], v[118:121]
	v_mfma_f32_16x16x32_bf16 v[114:117], v[176:179], v[184:187], v[114:117]
	v_mfma_f32_16x16x32_bf16 v[102:105], v[168:171], v[192:195], v[102:105]
	v_mfma_f32_16x16x32_bf16 v[98:101], v[176:179], v[192:195], v[98:101]
	v_mfma_f32_16x16x32_bf16 v[86:89], v[168:171], v[200:203], v[86:89]
	v_mfma_f32_16x16x32_bf16 v[82:85], v[176:179], v[200:203], v[82:85]
	v_mfma_f32_16x16x32_bf16 v[70:73], v[168:171], v[212:215], v[70:73]
	v_mfma_f32_16x16x32_bf16 v[66:69], v[176:179], v[212:215], v[66:69]
	v_mfma_f32_16x16x32_bf16 v[118:121], v[172:175], v[188:191], v[118:121]
	v_mfma_f32_16x16x32_bf16 v[114:117], v[180:183], v[188:191], v[114:117]
	v_mfma_f32_16x16x32_bf16 v[102:105], v[172:175], v[196:199], v[102:105]
	v_mfma_f32_16x16x32_bf16 v[98:101], v[180:183], v[196:199], v[98:101]
	v_mfma_f32_16x16x32_bf16 v[86:89], v[172:175], v[208:211], v[86:89]
	v_mfma_f32_16x16x32_bf16 v[82:85], v[180:183], v[208:211], v[82:85]
	v_mfma_f32_16x16x32_bf16 v[70:73], v[172:175], v[216:219], v[70:73]
	v_mfma_f32_16x16x32_bf16 v[66:69], v[180:183], v[216:219], v[66:69]
	s_barrier
	s_add_i32 s48, s74, s30
	s_mov_b32 m0, s48
	ds_read_b128 v[184:187], v154 offset:49152
	ds_read_b128 v[188:191], v154 offset:50176
	ds_read_b128 v[192:195], v154 offset:51200
	ds_read_b128 v[196:199], v154 offset:52224
	ds_read_b128 v[200:203], v154 offset:53248
	ds_read_b128 v[208:211], v154 offset:54272
	ds_read_b128 v[212:215], v154 offset:55296
	ds_read_b128 v[216:219], v154 offset:56320
	s_add_u32 s98, s46, s14
	s_addc_u32 s99, s47, s15
	s_add_i32 m0, s48, 0x2000
	s_add_u32 s46, s46, 0x40080
	v_lshl_add_u64 v[204:205], v[220:221], 0, s[14:15]
	s_addc_u32 s47, s47, 0
	s_add_i32 s48, s75, s30
	s_mov_b32 m0, s48
	s_nop 0
	s_add_i32 m0, s48, 0x2000
	s_nop 0
	v_lshl_add_u64 v[204:205], v[222:223], 0, s[14:15]
	s_mov_b32 m0, s62
	s_nop 0
	v_lshl_add_u64 v[204:205], v[224:225], 0, s[14:15]
	s_mov_b32 m0, s63
	s_nop 0
	s_bitcmp1_b32 s16, 0
	s_cbranch_scc1 .Lnlt_646_7
	s_waitcnt lgkmcnt(0)
.Lnlt_646_7:
	s_barrier
	s_waitcnt lgkmcnt(0)
	v_mfma_f32_16x16x32_bf16 v[62:65], v[148:151], v[184:187], v[62:65]
	v_mfma_f32_16x16x32_bf16 v[58:61], v[160:163], v[184:187], v[58:61]
	v_mfma_f32_16x16x32_bf16 v[46:49], v[148:151], v[192:195], v[46:49]
	v_mfma_f32_16x16x32_bf16 v[42:45], v[160:163], v[192:195], v[42:45]
	v_mfma_f32_16x16x32_bf16 v[30:33], v[148:151], v[200:203], v[30:33]
	v_mfma_f32_16x16x32_bf16 v[26:29], v[160:163], v[200:203], v[26:29]
	v_mfma_f32_16x16x32_bf16 v[14:17], v[148:151], v[212:215], v[14:17]
	v_mfma_f32_16x16x32_bf16 v[10:13], v[160:163], v[212:215], v[10:13]
	v_mfma_f32_16x16x32_bf16 v[62:65], v[156:159], v[188:191], v[62:65]
	v_mfma_f32_16x16x32_bf16 v[58:61], v[164:167], v[188:191], v[58:61]
	v_mfma_f32_16x16x32_bf16 v[46:49], v[156:159], v[196:199], v[46:49]
	v_mfma_f32_16x16x32_bf16 v[42:45], v[164:167], v[196:199], v[42:45]
	v_mfma_f32_16x16x32_bf16 v[30:33], v[156:159], v[208:211], v[30:33]
	v_mfma_f32_16x16x32_bf16 v[26:29], v[164:167], v[208:211], v[26:29]
	v_mfma_f32_16x16x32_bf16 v[14:17], v[156:159], v[216:219], v[14:17]
	v_mfma_f32_16x16x32_bf16 v[10:13], v[164:167], v[216:219], v[10:13]
	v_mfma_f32_16x16x32_bf16 v[54:57], v[168:171], v[184:187], v[54:57]
	v_mfma_f32_16x16x32_bf16 v[50:53], v[176:179], v[184:187], v[50:53]
	v_mfma_f32_16x16x32_bf16 v[38:41], v[168:171], v[192:195], v[38:41]
	v_mfma_f32_16x16x32_bf16 v[34:37], v[176:179], v[192:195], v[34:37]
	v_mfma_f32_16x16x32_bf16 v[22:25], v[168:171], v[200:203], v[22:25]
	v_mfma_f32_16x16x32_bf16 v[18:21], v[176:179], v[200:203], v[18:21]
	v_mfma_f32_16x16x32_bf16 v[6:9], v[168:171], v[212:215], v[6:9]
	v_mfma_f32_16x16x32_bf16 v[2:5], v[176:179], v[212:215], v[2:5]
	v_mfma_f32_16x16x32_bf16 v[54:57], v[172:175], v[188:191], v[54:57]
	v_mfma_f32_16x16x32_bf16 v[50:53], v[180:183], v[188:191], v[50:53]
	v_mfma_f32_16x16x32_bf16 v[38:41], v[172:175], v[196:199], v[38:41]
	v_mfma_f32_16x16x32_bf16 v[34:37], v[180:183], v[196:199], v[34:37]
	v_mfma_f32_16x16x32_bf16 v[22:25], v[172:175], v[208:211], v[22:25]
	v_mfma_f32_16x16x32_bf16 v[18:21], v[180:183], v[208:211], v[18:21]
	v_mfma_f32_16x16x32_bf16 v[6:9], v[172:175], v[216:219], v[6:9]
	v_mfma_f32_16x16x32_bf16 v[2:5], v[180:183], v[216:219], v[2:5]
	s_add_i32 s73, s73, 2
	s_add_u32 s44, s44, 0x100
	s_addc_u32 s45, s45, 0
	s_add_u32 s71, s71, 0x100
	s_addc_u32 s72, s72, 0
	s_barrier
.Ltl_646_done:
	s_and_b64 vcc, exec, s[16:17]
	s_cbranch_vccz .LBB0_649
	s_barrier

; #define PG8_STAGE(bufoff, gbase, voff) do { _Pragma("unroll") for (int _i = 0; _i < 2; ++_i) \
;         __builtin_amdgcn_global_load_lds((const unsigned*)((const char*)(gbase) + (voff)[_i]), (PG8_LAS unsigned*)(lds + (bufoff) + ldsw + _i * 8192), 16, 0, 0); } while (0)
; #define PG8_LDA(dst, b, h) do { _Pragma("unroll") for (int m = 0; m < 4; ++m) _Pragma("unroll") for (int k = 0; k < 2; ++k) dst[m][k] = *(const PG8_LAS bf16x8*)(lds + PG8_SA(b, h) + aoff + m * 2048 + k * 1024); } while (0)
; #define PG8_LDB(dst, b, h) do { _Pragma("unroll") for (int n = 0; n < 2; ++n) _Pragma("unroll") for (int k = 0; k < 2; ++k) dst[n][k] = *(const PG8_LAS bf16x8*)(lds + PG8_SB(b, h) + boff + n * 2048 + k * 1024); } while (0)
; #define PG8_MMA(ai, bj, At, Bt) do { __builtin_amdgcn_s_setprio(1); _Pragma("unroll") for (int m = 0; m < 4; ++m) _Pragma("unroll") for (int n = 0; n < 2; ++n) _Pragma("unroll") for (int k = 0; k < 2; ++k) \
;         acc[ai][bj][m][n] = __builtin_amdgcn_mfma_f32_16x16x32_bf16(Bt[n][k], At[m][k], acc[ai][bj][m][n], 0, 0, 0); __builtin_amdgcn_s_setprio(0); } while (0)
; #define PG8_WAIT_V(n) asm volatile("s_waitcnt vmcnt(" #n ")" ::: "memory")
; #define PG8_BAR __builtin_amdgcn_s_barrier()
; template <class Epi, class Sched, bool ALIGN_EPI = false, bool SP2 = false>
; __device__ __forceinline__ void gemm_phase(PG8_LAS unsigned char* lds, const Gemm g, const Sched& S, const Epi& E) {
;     ...
;         for (int t = 0; t < nt; t += 2) {
;             const bool last = (t == nt - 2);
;             const char* a1 = cA + (size_t)(t + 1) * kstep;
;             const char* a2 = last ? nA : cA + (size_t)(t + 2) * kstep; const char* b2 = last ? nB : cB + (size_t)(t + 2) * kstep;
;             const char* a3 = a2 + kstep; const char* b3 = b2 + kstep;
;             if (last && has_next) S.a_ready(nxt);
;             if constexpr (SP2) {
;             PG8_LDB(B0, 0, 0); PG8_LDB(B1, 0, 1); PG8_SCHED; PG8_LDA(At, 0, 0); PG8_STAGE(PG8_SA(1, 1), a1 + hstep, voffA);
;             PG8_WAIT_V(8); PG8_WAIT_L(0); PG8_BAR; PG8_MMA(0, 0, At, B0); PG8_MMA(0, 1, At, B1); PG8_BAR; PG8_SCHED;
;             PG8_LDA(At, 0, 1); PG8_STAGE(PG8_SB(0, 0), b2, voffB); PG8_STAGE(PG8_SB(0, 1), b2 + hstep, voffB); PG8_STAGE(PG8_SA(0, 0), a2, voffA);
;             PG8_WAIT_V(8); PG8_WAIT_L(0); PG8_BAR; PG8_MMA(1, 0, At, B0); PG8_MMA(1, 1, At, B1); PG8_BAR; PG8_SCHED;
.Lnl_740_7:
	s_barrier
	s_waitcnt lgkmcnt(0)
	v_mfma_f32_16x16x32_bf16 v[62:65], v[156:159], v[188:191], v[62:65]
	v_mfma_f32_16x16x32_bf16 v[58:61], v[164:167], v[188:191], v[58:61]
	v_mfma_f32_16x16x32_bf16 v[46:49], v[156:159], v[196:199], v[46:49]
	v_mfma_f32_16x16x32_bf16 v[42:45], v[164:167], v[196:199], v[42:45]
	v_mfma_f32_16x16x32_bf16 v[30:33], v[156:159], v[208:211], v[30:33]
	v_mfma_f32_16x16x32_bf16 v[26:29], v[164:167], v[208:211], v[26:29]
	v_mfma_f32_16x16x32_bf16 v[14:17], v[156:159], v[216:219], v[14:17]
	v_mfma_f32_16x16x32_bf16 v[10:13], v[164:167], v[216:219], v[10:13]
	v_mfma_f32_16x16x32_bf16 v[62:65], v[160:163], v[192:195], v[62:65]
	v_mfma_f32_16x16x32_bf16 v[58:61], v[168:171], v[192:195], v[58:61]
	v_mfma_f32_16x16x32_bf16 v[46:49], v[160:163], v[200:203], v[46:49]
	v_mfma_f32_16x16x32_bf16 v[42:45], v[168:171], v[200:203], v[42:45]
	v_mfma_f32_16x16x32_bf16 v[30:33], v[160:163], v[212:215], v[30:33]
	v_mfma_f32_16x16x32_bf16 v[26:29], v[168:171], v[212:215], v[26:29]
	v_mfma_f32_16x16x32_bf16 v[14:17], v[160:163], v[220:223], v[14:17]
	v_mfma_f32_16x16x32_bf16 v[10:13], v[168:171], v[220:223], v[10:13]
	v_mfma_f32_16x16x32_bf16 v[54:57], v[172:175], v[188:191], v[54:57]
	v_mfma_f32_16x16x32_bf16 v[50:53], v[180:183], v[188:191], v[50:53]
	v_mfma_f32_16x16x32_bf16 v[38:41], v[172:175], v[196:199], v[38:41]
	v_mfma_f32_16x16x32_bf16 v[34:37], v[180:183], v[196:199], v[34:37]
	v_mfma_f32_16x16x32_bf16 v[22:25], v[172:175], v[208:211], v[22:25]
	v_mfma_f32_16x16x32_bf16 v[18:21], v[180:183], v[208:211], v[18:21]
	v_mfma_f32_16x16x32_bf16 v[6:9], v[172:175], v[216:219], v[6:9]
	v_mfma_f32_16x16x32_bf16 v[2:5], v[180:183], v[216:219], v[2:5]
	v_mfma_f32_16x16x32_bf16 v[54:57], v[176:179], v[192:195], v[54:57]
	v_mfma_f32_16x16x32_bf16 v[50:53], v[184:187], v[192:195], v[50:53]
	v_mfma_f32_16x16x32_bf16 v[38:41], v[176:179], v[200:203], v[38:41]
	v_mfma_f32_16x16x32_bf16 v[34:37], v[184:187], v[200:203], v[34:37]
	v_mfma_f32_16x16x32_bf16 v[22:25], v[176:179], v[212:215], v[22:25]
	v_mfma_f32_16x16x32_bf16 v[18:21], v[184:187], v[212:215], v[18:21]
	v_mfma_f32_16x16x32_bf16 v[6:9], v[176:179], v[220:223], v[6:9]
	v_mfma_f32_16x16x32_bf16 v[2:5], v[184:187], v[220:223], v[2:5]
	s_add_i32 s71, s71, 2
	s_add_u32 s30, s30, 0x100
	s_addc_u32 s31, s31, 0
	s_add_u32 s33, s33, 0x100
	s_addc_u32 s70, s70, 0
	s_cmp_gt_u32 s71, 11
	s_barrier
	s_cbranch_scc0 .LBB0_740
	s_cmp_gt_u32 s71, 13
	s_cbranch_scc1 .Ltl_740_done
	s_cmp_lg_u64 s[0:1], 0
	s_cbranch_scc1 .LBB0_740
	ds_read_b128 v[156:159], v152
	ds_read_b128 v[160:163], v152 offset:1024
	ds_read_b128 v[164:167], v152 offset:2048
	ds_read_b128 v[168:171], v152 offset:3072
	ds_read_b128 v[172:175], v153
	ds_read_b128 v[176:179], v153 offset:1024
	ds_read_b128 v[180:183], v153 offset:2048
	ds_read_b128 v[184:187], v153 offset:3072
	s_add_u32 s40, s30, 0xfffc0080
	s_addc_u32 s41, s31, -1
	s_cmp_eq_u32 s71, 12
	s_cselect_b32 s45, s19, s41
	s_cselect_b32 s44, s25, s40
	s_cselect_b32 s41, s17, s70
	s_cselect_b32 s40, s27, s33
	v_lshl_add_u64 v[148:149], s[30:31], 0, v[140:141]
	s_add_i32 m0, s48, 0xc000
	ds_read_b128 v[188:191], v154
	ds_read_b128 v[192:195], v154 offset:1024
	ds_read_b128 v[196:199], v154 offset:2048
	ds_read_b128 v[200:203], v154 offset:3072
	ds_read_b128 v[208:211], v154 offset:4096
	ds_read_b128 v[212:215], v154 offset:5120
	ds_read_b128 v[216:219], v154 offset:6144
	ds_read_b128 v[220:223], v154 offset:7168
	global_load_lds_dwordx4 v[148:149], off
	v_lshl_add_u64 v[148:149], s[30:31], 0, v[142:143]
	s_add_i32 m0, s48, 0xe000
	s_nop 0
	global_load_lds_dwordx4 v[148:149], off
	s_waitcnt vmcnt(8)
	s_bitcmp1_b32 s14, 0
	s_cbranch_scc1 .Lnlt_740_4
	s_waitcnt lgkmcnt(0)
.Lnlt_740_4:
	s_barrier
	s_waitcnt lgkmcnt(0)
	v_mfma_f32_16x16x32_bf16 v[126:129], v[156:159], v[188:191], v[126:129]
	v_mfma_f32_16x16x32_bf16 v[122:125], v[164:167], v[188:191], v[122:125]
	v_mfma_f32_16x16x32_bf16 v[110:113], v[156:159], v[196:199], v[110:113]
	v_mfma_f32_16x16x32_bf16 v[106:109], v[164:167], v[196:199], v[106:109]
	v_mfma_f32_16x16x32_bf16 v[94:97], v[156:159], v[208:211], v[94:97]
	v_mfma_f32_16x16x32_bf16 v[90:93], v[164:167], v[208:211], v[90:93]
	v_mfma_f32_16x16x32_bf16 v[78:81], v[156:159], v[216:219], v[78:81]
	v_mfma_f32_16x16x32_bf16 v[74:77], v[164:167], v[216:219], v[74:77]
	v_mfma_f32_16x16x32_bf16 v[126:129], v[160:163], v[192:195], v[126:129]
	v_mfma_f32_16x16x32_bf16 v[122:125], v[168:171], v[192:195], v[122:125]
	v_mfma_f32_16x16x32_bf16 v[110:113], v[160:163], v[200:203], v[110:113]
	v_mfma_f32_16x16x32_bf16 v[106:109], v[168:171], v[200:203], v[106:109]
	v_mfma_f32_16x16x32_bf16 v[94:97], v[160:163], v[212:215], v[94:97]
	v_mfma_f32_16x16x32_bf16 v[90:93], v[168:171], v[212:215], v[90:93]
	v_mfma_f32_16x16x32_bf16 v[78:81], v[160:163], v[220:223], v[78:81]
	v_mfma_f32_16x16x32_bf16 v[74:77], v[168:171], v[220:223], v[74:77]
	v_mfma_f32_16x16x32_bf16 v[118:121], v[172:175], v[188:191], v[118:121]
	v_mfma_f32_16x16x32_bf16 v[114:117], v[180:183], v[188:191], v[114:117]
	v_mfma_f32_16x16x32_bf16 v[102:105], v[172:175], v[196:199], v[102:105]
	v_mfma_f32_16x16x32_bf16 v[98:101], v[180:183], v[196:199], v[98:101]
	v_mfma_f32_16x16x32_bf16 v[86:89], v[172:175], v[208:211], v[86:89]
	v_mfma_f32_16x16x32_bf16 v[82:85], v[180:183], v[208:211], v[82:85]
	v_mfma_f32_16x16x32_bf16 v[70:73], v[172:175], v[216:219], v[70:73]
	v_mfma_f32_16x16x32_bf16 v[66:69], v[180:183], v[216:219], v[66:69]
	v_mfma_f32_16x16x32_bf16 v[118:121], v[176:179], v[192:195], v[118:121]
	v_mfma_f32_16x16x32_bf16 v[114:117], v[184:187], v[192:195], v[114:117]
	v_mfma_f32_16x16x32_bf16 v[102:105], v[176:179], v[200:203], v[102:105]
	v_mfma_f32_16x16x32_bf16 v[98:101], v[184:187], v[200:203], v[98:101]
	v_mfma_f32_16x16x32_bf16 v[86:89], v[176:179], v[212:215], v[86:89]
	v_mfma_f32_16x16x32_bf16 v[82:85], v[184:187], v[212:215], v[82:85]
	v_mfma_f32_16x16x32_bf16 v[70:73], v[176:179], v[220:223], v[70:73]
	v_mfma_f32_16x16x32_bf16 v[66:69], v[184:187], v[220:223], v[66:69]
	s_barrier
	s_add_i32 s72, s66, s47
	s_mov_b32 m0, s72
	ds_read_b128 v[188:191], v154 offset:16384
	ds_read_b128 v[192:195], v154 offset:17408
	ds_read_b128 v[196:199], v154 offset:18432
	ds_read_b128 v[200:203], v154 offset:19456
	ds_read_b128 v[208:211], v154 offset:20480
	ds_read_b128 v[212:215], v154 offset:21504
	ds_read_b128 v[216:219], v154 offset:22528
	ds_read_b128 v[220:223], v154 offset:23552
	s_add_i32 m0, s72, 0x2000
	s_add_u32 s72, s40, 0x40000
	v_lshl_add_u64 v[204:205], s[40:41], 0, v[136:137]
	s_addc_u32 s73, s41, 0
	s_add_i32 s74, s67, s47
	s_mov_b32 m0, s74
	v_lshl_add_u64 v[226:227], s[44:45], 0, v[134:135]
	s_add_i32 m0, s74, 0x2000
	s_nop 0
	v_lshl_add_u64 v[224:225], s[44:45], 0, v[130:131]
	s_mov_b32 m0, s48
	s_nop 0
	s_mov_b32 m0, s49
	s_nop 0
	s_waitcnt vmcnt(2)
	s_bitcmp1_b32 s14, 0
	s_cbranch_scc1 .Lnlt_740_5
	s_waitcnt lgkmcnt(0)
; #define PG8_STAGE(bufoff, gbase, voff) do { _Pragma("unroll") for (int _i = 0; _i < 2; ++_i) \
;         __builtin_amdgcn_global_load_lds((const unsigned*)((const char*)(gbase) + (voff)[_i]), (PG8_LAS unsigned*)(lds + (bufoff) + ldsw + _i * 8192), 16, 0, 0); } while (0)
; #define PG8_LDA(dst, b, h) do { _Pragma("unroll") for (int m = 0; m < 4; ++m) _Pragma("unroll") for (int k = 0; k < 2; ++k) dst[m][k] = *(const PG8_LAS bf16x8*)(lds + PG8_SA(b, h) + aoff + m * 2048 + k * 1024); } while (0)
; #define PG8_LDB(dst, b, h) do { _Pragma("unroll") for (int n = 0; n < 2; ++n) _Pragma("unroll") for (int k = 0; k < 2; ++k) dst[n][k] = *(const PG8_LAS bf16x8*)(lds + PG8_SB(b, h) + boff + n * 2048 + k * 1024); } while (0)
; #define PG8_MMA(ai, bj, At, Bt) do { __builtin_amdgcn_s_setprio(1); _Pragma("unroll") for (int m = 0; m < 4; ++m) _Pragma("unroll") for (int n = 0; n < 2; ++n) _Pragma("unroll") for (int k = 0; k < 2; ++k) \
;         acc[ai][bj][m][n] = __builtin_amdgcn_mfma_f32_16x16x32_bf16(Bt[n][k], At[m][k], acc[ai][bj][m][n], 0, 0, 0); __builtin_amdgcn_s_setprio(0); } while (0)
; #define PG8_WAIT_V(n) asm volatile("s_waitcnt vmcnt(" #n ")" ::: "memory")
; #define PG8_WAIT_L(n) asm volatile("s_waitcnt lgkmcnt(" #n ")" ::: "memory")
; #define PG8_BAR __builtin_amdgcn_s_barrier()
; #define PG8_SCHED __builtin_amdgcn_sched_barrier(0)
; template <class Epi, class Sched, bool ALIGN_EPI = false, bool SP2 = false>
; __device__ __forceinline__ void gemm_phase(PG8_LAS unsigned char* lds, const Gemm g, const Sched& S, const Epi& E) {
;     ...
;             PG8_WAIT_V(8); PG8_WAIT_L(0); PG8_BAR; PG8_MMA(1, 0, At, B0); PG8_MMA(1, 1, At, B1); PG8_BAR; PG8_SCHED;
;             PG8_LDB(B0, 1, 0); PG8_LDB(B1, 1, 1); PG8_SCHED; PG8_LDA(At, 1, 0); PG8_STAGE(PG8_SA(0, 1), a2 + hstep, voffA);
;             PG8_WAIT_V(8); PG8_WAIT_L(0); PG8_BAR; PG8_MMA(0, 0, At, B0); PG8_MMA(0, 1, At, B1); PG8_BAR; PG8_SCHED;
.Lnlt_740_5:
	s_barrier
	s_waitcnt lgkmcnt(0)
	v_mfma_f32_16x16x32_bf16 v[62:65], v[156:159], v[188:191], v[62:65]
	v_mfma_f32_16x16x32_bf16 v[58:61], v[164:167], v[188:191], v[58:61]
	v_mfma_f32_16x16x32_bf16 v[46:49], v[156:159], v[196:199], v[46:49]
	v_mfma_f32_16x16x32_bf16 v[42:45], v[164:167], v[196:199], v[42:45]
	v_mfma_f32_16x16x32_bf16 v[30:33], v[156:159], v[208:211], v[30:33]
	v_mfma_f32_16x16x32_bf16 v[26:29], v[164:167], v[208:211], v[26:29]
	v_mfma_f32_16x16x32_bf16 v[14:17], v[156:159], v[216:219], v[14:17]
	v_mfma_f32_16x16x32_bf16 v[10:13], v[164:167], v[216:219], v[10:13]
	v_mfma_f32_16x16x32_bf16 v[62:65], v[160:163], v[192:195], v[62:65]
	v_mfma_f32_16x16x32_bf16 v[58:61], v[168:171], v[192:195], v[58:61]
	v_mfma_f32_16x16x32_bf16 v[46:49], v[160:163], v[200:203], v[46:49]
	v_mfma_f32_16x16x32_bf16 v[42:45], v[168:171], v[200:203], v[42:45]
	v_mfma_f32_16x16x32_bf16 v[30:33], v[160:163], v[212:215], v[30:33]
	v_mfma_f32_16x16x32_bf16 v[26:29], v[168:171], v[212:215], v[26:29]
	v_mfma_f32_16x16x32_bf16 v[14:17], v[160:163], v[220:223], v[14:17]
	v_mfma_f32_16x16x32_bf16 v[10:13], v[168:171], v[220:223], v[10:13]
	v_mfma_f32_16x16x32_bf16 v[54:57], v[172:175], v[188:191], v[54:57]
	v_mfma_f32_16x16x32_bf16 v[50:53], v[180:183], v[188:191], v[50:53]
	v_mfma_f32_16x16x32_bf16 v[38:41], v[172:175], v[196:199], v[38:41]
	v_mfma_f32_16x16x32_bf16 v[34:37], v[180:183], v[196:199], v[34:37]
	v_mfma_f32_16x16x32_bf16 v[22:25], v[172:175], v[208:211], v[22:25]
	v_mfma_f32_16x16x32_bf16 v[18:21], v[180:183], v[208:211], v[18:21]
	v_mfma_f32_16x16x32_bf16 v[6:9], v[172:175], v[216:219], v[6:9]
	v_mfma_f32_16x16x32_bf16 v[2:5], v[180:183], v[216:219], v[2:5]
	v_mfma_f32_16x16x32_bf16 v[54:57], v[176:179], v[192:195], v[54:57]
	v_mfma_f32_16x16x32_bf16 v[50:53], v[184:187], v[192:195], v[50:53]
	v_mfma_f32_16x16x32_bf16 v[38:41], v[176:179], v[200:203], v[38:41]
	v_mfma_f32_16x16x32_bf16 v[34:37], v[184:187], v[200:203], v[34:37]
	v_mfma_f32_16x16x32_bf16 v[22:25], v[176:179], v[212:215], v[22:25]
	v_mfma_f32_16x16x32_bf16 v[18:21], v[184:187], v[212:215], v[18:21]
	v_mfma_f32_16x16x32_bf16 v[6:9], v[176:179], v[220:223], v[6:9]
	v_mfma_f32_16x16x32_bf16 v[2:5], v[184:187], v[220:223], v[2:5]
	s_barrier
	s_add_i32 s72, 0, 0x18000
	v_add_u32_e32 v150, s72, v151
	s_add_i32 s73, 0, 0x1c000
	ds_read_b128 v[156:159], v150
	ds_read_b128 v[160:163], v150 offset:1024
	ds_read_b128 v[164:167], v150 offset:2048
	ds_read_b128 v[168:171], v150 offset:3072
	v_add_u32_e32 v150, s73, v151
	ds_read_b128 v[172:175], v150
	ds_read_b128 v[176:179], v150 offset:1024
	ds_read_b128 v[180:183], v150 offset:2048
	ds_read_b128 v[184:187], v150 offset:3072
	s_add_u32 s44, s44, 0x40000
	s_addc_u32 s45, s45, 0
	s_mov_b32 m0, s50
	ds_read_b128 v[188:191], v154 offset:32768
	ds_read_b128 v[192:195], v154 offset:33792
	ds_read_b128 v[196:199], v154 offset:34816
	ds_read_b128 v[200:203], v154 offset:35840
	ds_read_b128 v[208:211], v154 offset:36864
	ds_read_b128 v[212:215], v154 offset:37888
	ds_read_b128 v[216:219], v154 offset:38912
	ds_read_b128 v[220:223], v154 offset:39936
	s_mov_b32 m0, s51
	s_nop 0
	s_waitcnt vmcnt(0)
	s_bitcmp1_b32 s14, 0
	s_cbranch_scc1 .Lnlt_740_6
	s_waitcnt lgkmcnt(0)
; #define PG8_STAGE(bufoff, gbase, voff) do { _Pragma("unroll") for (int _i = 0; _i < 2; ++_i) \
;         __builtin_amdgcn_global_load_lds((const unsigned*)((const char*)(gbase) + (voff)[_i]), (PG8_LAS unsigned*)(lds + (bufoff) + ldsw + _i * 8192), 16, 0, 0); } while (0)
; #define PG8_LDA(dst, b, h) do { _Pragma("unroll") for (int m = 0; m < 4; ++m) _Pragma("unroll") for (int k = 0; k < 2; ++k) dst[m][k] = *(const PG8_LAS bf16x8*)(lds + PG8_SA(b, h) + aoff + m * 2048 + k * 1024); } while (0)
; #define PG8_MMA(ai, bj, At, Bt) do { __builtin_amdgcn_s_setprio(1); _Pragma("unroll") for (int m = 0; m < 4; ++m) _Pragma("unroll") for (int n = 0; n < 2; ++n) _Pragma("unroll") for (int k = 0; k < 2; ++k) \
;         acc[ai][bj][m][n] = __builtin_amdgcn_mfma_f32_16x16x32_bf16(Bt[n][k], At[m][k], acc[ai][bj][m][n], 0, 0, 0); __builtin_amdgcn_s_setprio(0); } while (0)
; #define PG8_WAIT_V(n) asm volatile("s_waitcnt vmcnt(" #n ")" ::: "memory")
; #define PG8_WAIT_L(n) asm volatile("s_waitcnt lgkmcnt(" #n ")" ::: "memory")
; #define PG8_BAR __builtin_amdgcn_s_barrier()
; #define PG8_SCHED __builtin_amdgcn_sched_barrier(0)
; template <class Epi, class Sched, bool ALIGN_EPI = false, bool SP2 = false>
; __device__ __forceinline__ void gemm_phase(PG8_LAS unsigned char* lds, const Gemm g, const Sched& S, const Epi& E) {
;     ...
;             PG8_WAIT_V(8); PG8_WAIT_L(0); PG8_BAR; PG8_MMA(0, 0, At, B0); PG8_MMA(0, 1, At, B1); PG8_BAR; PG8_SCHED;
;             PG8_LDA(At, 1, 1); PG8_STAGE(PG8_SB(1, 0), b3, voffB); PG8_STAGE(PG8_SB(1, 1), b3 + hstep, voffB); PG8_STAGE(PG8_SA(1, 0), a3, voffA);
;             PG8_WAIT_V(8); PG8_WAIT_L(0); PG8_BAR; PG8_MMA(1, 0, At, B0); PG8_MMA(1, 1, At, B1); PG8_BAR; PG8_SCHED;
;     ...
;         if constexpr (ALIGN_EPI) { if (wr == 0) PG8_BAR; }
.Lnlt_740_6:
	s_barrier
	s_waitcnt lgkmcnt(0)
	v_mfma_f32_16x16x32_bf16 v[126:129], v[156:159], v[188:191], v[126:129]
	v_mfma_f32_16x16x32_bf16 v[122:125], v[164:167], v[188:191], v[122:125]
	v_mfma_f32_16x16x32_bf16 v[110:113], v[156:159], v[196:199], v[110:113]
	v_mfma_f32_16x16x32_bf16 v[106:109], v[164:167], v[196:199], v[106:109]
	v_mfma_f32_16x16x32_bf16 v[94:97], v[156:159], v[208:211], v[94:97]
	v_mfma_f32_16x16x32_bf16 v[90:93], v[164:167], v[208:211], v[90:93]
	v_mfma_f32_16x16x32_bf16 v[78:81], v[156:159], v[216:219], v[78:81]
	v_mfma_f32_16x16x32_bf16 v[74:77], v[164:167], v[216:219], v[74:77]
	v_mfma_f32_16x16x32_bf16 v[126:129], v[160:163], v[192:195], v[126:129]
	v_mfma_f32_16x16x32_bf16 v[122:125], v[168:171], v[192:195], v[122:125]
	v_mfma_f32_16x16x32_bf16 v[110:113], v[160:163], v[200:203], v[110:113]
	v_mfma_f32_16x16x32_bf16 v[106:109], v[168:171], v[200:203], v[106:109]
	v_mfma_f32_16x16x32_bf16 v[94:97], v[160:163], v[212:215], v[94:97]
	v_mfma_f32_16x16x32_bf16 v[90:93], v[168:171], v[212:215], v[90:93]
	v_mfma_f32_16x16x32_bf16 v[78:81], v[160:163], v[220:223], v[78:81]
	v_mfma_f32_16x16x32_bf16 v[74:77], v[168:171], v[220:223], v[74:77]
	v_mfma_f32_16x16x32_bf16 v[118:121], v[172:175], v[188:191], v[118:121]
	v_mfma_f32_16x16x32_bf16 v[114:117], v[180:183], v[188:191], v[114:117]
	v_mfma_f32_16x16x32_bf16 v[102:105], v[172:175], v[196:199], v[102:105]
	v_mfma_f32_16x16x32_bf16 v[98:101], v[180:183], v[196:199], v[98:101]
	v_mfma_f32_16x16x32_bf16 v[86:89], v[172:175], v[208:211], v[86:89]
	v_mfma_f32_16x16x32_bf16 v[82:85], v[180:183], v[208:211], v[82:85]
	v_mfma_f32_16x16x32_bf16 v[70:73], v[172:175], v[216:219], v[70:73]
	v_mfma_f32_16x16x32_bf16 v[66:69], v[180:183], v[216:219], v[66:69]
	v_mfma_f32_16x16x32_bf16 v[118:121], v[176:179], v[192:195], v[118:121]
	v_mfma_f32_16x16x32_bf16 v[114:117], v[184:187], v[192:195], v[114:117]
	v_mfma_f32_16x16x32_bf16 v[102:105], v[176:179], v[200:203], v[102:105]
	v_mfma_f32_16x16x32_bf16 v[98:101], v[184:187], v[200:203], v[98:101]
	v_mfma_f32_16x16x32_bf16 v[86:89], v[176:179], v[212:215], v[86:89]
	v_mfma_f32_16x16x32_bf16 v[82:85], v[184:187], v[212:215], v[82:85]
	v_mfma_f32_16x16x32_bf16 v[70:73], v[176:179], v[220:223], v[70:73]
	v_mfma_f32_16x16x32_bf16 v[66:69], v[184:187], v[220:223], v[66:69]
	s_barrier
	s_add_i32 s44, s72, s47
	s_mov_b32 m0, s44
	ds_read_b128 v[188:191], v154 offset:49152
	ds_read_b128 v[192:195], v154 offset:50176
	ds_read_b128 v[196:199], v154 offset:51200
	ds_read_b128 v[200:203], v154 offset:52224
	ds_read_b128 v[208:211], v154 offset:53248
	ds_read_b128 v[212:215], v154 offset:54272
	ds_read_b128 v[216:219], v154 offset:55296
	ds_read_b128 v[220:223], v154 offset:56320
	s_add_u32 s98, s40, s12
	s_addc_u32 s99, s41, s13
	s_add_i32 m0, s44, 0x2000
	s_add_u32 s40, s40, 0x40080
	v_lshl_add_u64 v[148:149], v[204:205], 0, s[12:13]
	s_addc_u32 s41, s41, 0
	s_add_i32 s44, s73, s47
	s_mov_b32 m0, s44
	s_nop 0
	s_add_i32 m0, s44, 0x2000
	s_nop 0
	v_lshl_add_u64 v[148:149], v[224:225], 0, s[12:13]
	s_mov_b32 m0, s61
	s_nop 0
	v_lshl_add_u64 v[148:149], v[226:227], 0, s[12:13]
	s_mov_b32 m0, s62
	s_nop 0
	s_bitcmp1_b32 s14, 0
	s_cbranch_scc1 .Lnlt_740_7
	s_waitcnt lgkmcnt(0)
.Lnlt_740_7:
	s_barrier
	s_waitcnt lgkmcnt(0)
	v_mfma_f32_16x16x32_bf16 v[62:65], v[156:159], v[188:191], v[62:65]
	v_mfma_f32_16x16x32_bf16 v[58:61], v[164:167], v[188:191], v[58:61]
	v_mfma_f32_16x16x32_bf16 v[46:49], v[156:159], v[196:199], v[46:49]
	v_mfma_f32_16x16x32_bf16 v[42:45], v[164:167], v[196:199], v[42:45]
	v_mfma_f32_16x16x32_bf16 v[30:33], v[156:159], v[208:211], v[30:33]
	v_mfma_f32_16x16x32_bf16 v[26:29], v[164:167], v[208:211], v[26:29]
	v_mfma_f32_16x16x32_bf16 v[14:17], v[156:159], v[216:219], v[14:17]
	v_mfma_f32_16x16x32_bf16 v[10:13], v[164:167], v[216:219], v[10:13]
	v_mfma_f32_16x16x32_bf16 v[62:65], v[160:163], v[192:195], v[62:65]
	v_mfma_f32_16x16x32_bf16 v[58:61], v[168:171], v[192:195], v[58:61]
	v_mfma_f32_16x16x32_bf16 v[46:49], v[160:163], v[200:203], v[46:49]
	v_mfma_f32_16x16x32_bf16 v[42:45], v[168:171], v[200:203], v[42:45]
	v_mfma_f32_16x16x32_bf16 v[30:33], v[160:163], v[212:215], v[30:33]
	v_mfma_f32_16x16x32_bf16 v[26:29], v[168:171], v[212:215], v[26:29]
	v_mfma_f32_16x16x32_bf16 v[14:17], v[160:163], v[220:223], v[14:17]
	v_mfma_f32_16x16x32_bf16 v[10:13], v[168:171], v[220:223], v[10:13]
	v_mfma_f32_16x16x32_bf16 v[54:57], v[172:175], v[188:191], v[54:57]
	v_mfma_f32_16x16x32_bf16 v[50:53], v[180:183], v[188:191], v[50:53]
	v_mfma_f32_16x16x32_bf16 v[38:41], v[172:175], v[196:199], v[38:41]
	v_mfma_f32_16x16x32_bf16 v[34:37], v[180:183], v[196:199], v[34:37]
	v_mfma_f32_16x16x32_bf16 v[22:25], v[172:175], v[208:211], v[22:25]
	v_mfma_f32_16x16x32_bf16 v[18:21], v[180:183], v[208:211], v[18:21]
	v_mfma_f32_16x16x32_bf16 v[6:9], v[172:175], v[216:219], v[6:9]
	v_mfma_f32_16x16x32_bf16 v[2:5], v[180:183], v[216:219], v[2:5]
	v_mfma_f32_16x16x32_bf16 v[54:57], v[176:179], v[192:195], v[54:57]
	v_mfma_f32_16x16x32_bf16 v[50:53], v[184:187], v[192:195], v[50:53]
	v_mfma_f32_16x16x32_bf16 v[38:41], v[176:179], v[200:203], v[38:41]
	v_mfma_f32_16x16x32_bf16 v[34:37], v[184:187], v[200:203], v[34:37]
	v_mfma_f32_16x16x32_bf16 v[22:25], v[176:179], v[212:215], v[22:25]
	v_mfma_f32_16x16x32_bf16 v[18:21], v[184:187], v[212:215], v[18:21]
	v_mfma_f32_16x16x32_bf16 v[6:9], v[176:179], v[220:223], v[6:9]
	v_mfma_f32_16x16x32_bf16 v[2:5], v[184:187], v[220:223], v[2:5]
	s_add_i32 s71, s71, 2
	s_add_u32 s30, s30, 0x100
	s_addc_u32 s31, s31, 0
	s_add_u32 s33, s33, 0x100
	s_addc_u32 s70, s70, 0
	s_barrier
.Ltl_740_done:
	s_and_b64 vcc, exec, s[14:15]
	s_cbranch_vccz .LBB0_743
	s_barrier

; #define PG8_STAGE(bufoff, gbase, voff) do { _Pragma("unroll") for (int _i = 0; _i < 2; ++_i) \
;         __builtin_amdgcn_global_load_lds((const unsigned*)((const char*)(gbase) + (voff)[_i]), (PG8_LAS unsigned*)(lds + (bufoff) + ldsw + _i * 8192), 16, 0, 0); } while (0)
; #define PG8_LDA(dst, b, h) do { _Pragma("unroll") for (int m = 0; m < 4; ++m) _Pragma("unroll") for (int k = 0; k < 2; ++k) dst[m][k] = *(const PG8_LAS bf16x8*)(lds + PG8_SA(b, h) + aoff + m * 2048 + k * 1024); } while (0)
; #define PG8_LDB(dst, b, h) do { _Pragma("unroll") for (int n = 0; n < 2; ++n) _Pragma("unroll") for (int k = 0; k < 2; ++k) dst[n][k] = *(const PG8_LAS bf16x8*)(lds + PG8_SB(b, h) + boff + n * 2048 + k * 1024); } while (0)
; #define PG8_MMA(ai, bj, At, Bt) do { __builtin_amdgcn_s_setprio(1); _Pragma("unroll") for (int m = 0; m < 4; ++m) _Pragma("unroll") for (int n = 0; n < 2; ++n) _Pragma("unroll") for (int k = 0; k < 2; ++k) \
;         acc[ai][bj][m][n] = __builtin_amdgcn_mfma_f32_16x16x32_bf16(Bt[n][k], At[m][k], acc[ai][bj][m][n], 0, 0, 0); __builtin_amdgcn_s_setprio(0); } while (0)
; #define PG8_WAIT_V(n) asm volatile("s_waitcnt vmcnt(" #n ")" ::: "memory")
; #define PG8_BAR __builtin_amdgcn_s_barrier()
; template <class Epi, class Sched, bool ALIGN_EPI = false, bool SP2 = false>
; __device__ __forceinline__ void gemm_phase(PG8_LAS unsigned char* lds, const Gemm g, const Sched& S, const Epi& E) {
;     ...
;         for (int t = 0; t < nt; t += 2) {
;             const bool last = (t == nt - 2);
;             const char* a1 = cA + (size_t)(t + 1) * kstep;
;             const char* a2 = last ? nA : cA + (size_t)(t + 2) * kstep; const char* b2 = last ? nB : cB + (size_t)(t + 2) * kstep;
;             const char* a3 = a2 + kstep; const char* b3 = b2 + kstep;
;             if (last && has_next) S.a_ready(nxt);
;             if constexpr (SP2) {
;             PG8_LDB(B0, 0, 0); PG8_LDB(B1, 0, 1); PG8_SCHED; PG8_LDA(At, 0, 0); PG8_STAGE(PG8_SA(1, 1), a1 + hstep, voffA);
;             PG8_WAIT_V(8); PG8_WAIT_L(0); PG8_BAR; PG8_MMA(0, 0, At, B0); PG8_MMA(0, 1, At, B1); PG8_BAR; PG8_SCHED;
;             PG8_LDA(At, 0, 1); PG8_STAGE(PG8_SB(0, 0), b2, voffB); PG8_STAGE(PG8_SB(0, 1), b2 + hstep, voffB); PG8_STAGE(PG8_SA(0, 0), a2, voffA);
;             PG8_WAIT_V(8); PG8_WAIT_L(0); PG8_BAR; PG8_MMA(1, 0, At, B0); PG8_MMA(1, 1, At, B1); PG8_BAR; PG8_SCHED;
.Lnl_861_7:
	s_barrier
	s_waitcnt lgkmcnt(0)
	v_mfma_f32_16x16x32_bf16 v[60:63], v[146:149], v[184:187], v[60:63]
	v_mfma_f32_16x16x32_bf16 v[56:59], v[160:163], v[184:187], v[56:59]
	v_mfma_f32_16x16x32_bf16 v[44:47], v[146:149], v[192:195], v[44:47]
	v_mfma_f32_16x16x32_bf16 v[40:43], v[160:163], v[192:195], v[40:43]
	v_mfma_f32_16x16x32_bf16 v[28:31], v[146:149], v[200:203], v[28:31]
	v_mfma_f32_16x16x32_bf16 v[24:27], v[160:163], v[200:203], v[24:27]
	v_mfma_f32_16x16x32_bf16 v[12:15], v[146:149], v[208:211], v[12:15]
	v_mfma_f32_16x16x32_bf16 v[8:11], v[160:163], v[208:211], v[8:11]
	v_mfma_f32_16x16x32_bf16 v[60:63], v[156:159], v[188:191], v[60:63]
	v_mfma_f32_16x16x32_bf16 v[56:59], v[164:167], v[188:191], v[56:59]
	v_mfma_f32_16x16x32_bf16 v[44:47], v[156:159], v[196:199], v[44:47]
	v_mfma_f32_16x16x32_bf16 v[40:43], v[164:167], v[196:199], v[40:43]
	v_mfma_f32_16x16x32_bf16 v[28:31], v[156:159], v[204:207], v[28:31]
	v_mfma_f32_16x16x32_bf16 v[24:27], v[164:167], v[204:207], v[24:27]
	v_mfma_f32_16x16x32_bf16 v[12:15], v[156:159], v[212:215], v[12:15]
	v_mfma_f32_16x16x32_bf16 v[8:11], v[164:167], v[212:215], v[8:11]
	v_mfma_f32_16x16x32_bf16 v[52:55], v[168:171], v[184:187], v[52:55]
	v_mfma_f32_16x16x32_bf16 v[48:51], v[176:179], v[184:187], v[48:51]
	v_mfma_f32_16x16x32_bf16 v[36:39], v[168:171], v[192:195], v[36:39]
	v_mfma_f32_16x16x32_bf16 v[32:35], v[176:179], v[192:195], v[32:35]
	v_mfma_f32_16x16x32_bf16 v[20:23], v[168:171], v[200:203], v[20:23]
	v_mfma_f32_16x16x32_bf16 v[16:19], v[176:179], v[200:203], v[16:19]
	v_mfma_f32_16x16x32_bf16 v[4:7], v[168:171], v[208:211], v[4:7]
	v_mfma_f32_16x16x32_bf16 v[0:3], v[176:179], v[208:211], v[0:3]
	v_mfma_f32_16x16x32_bf16 v[52:55], v[172:175], v[188:191], v[52:55]
	v_mfma_f32_16x16x32_bf16 v[48:51], v[180:183], v[188:191], v[48:51]
	v_mfma_f32_16x16x32_bf16 v[36:39], v[172:175], v[196:199], v[36:39]
	v_mfma_f32_16x16x32_bf16 v[32:35], v[180:183], v[196:199], v[32:35]
	v_mfma_f32_16x16x32_bf16 v[20:23], v[172:175], v[204:207], v[20:23]
	v_mfma_f32_16x16x32_bf16 v[16:19], v[180:183], v[204:207], v[16:19]
	v_mfma_f32_16x16x32_bf16 v[4:7], v[172:175], v[212:215], v[4:7]
	v_mfma_f32_16x16x32_bf16 v[0:3], v[180:183], v[212:215], v[0:3]
	s_add_i32 s53, s53, 2
	s_add_u32 s24, s24, 0x100
	s_addc_u32 s25, s25, 0
	s_add_u32 s51, s51, 0x100
	s_addc_u32 s52, s52, 0
	s_cmp_gt_u32 s53, 39
	s_barrier
	s_cbranch_scc0 .LBB0_861
	s_cmp_gt_u32 s53, 41
	s_cbranch_scc1 .Ltl_861_done
	s_cmp_eq_u64 s[0:1], 0
	s_cbranch_scc1 .LBB0_861
	ds_read_b128 v[146:149], v153
	ds_read_b128 v[156:159], v153 offset:1024
	ds_read_b128 v[160:163], v153 offset:2048
	ds_read_b128 v[164:167], v153 offset:3072
	ds_read_b128 v[168:171], v154
	ds_read_b128 v[172:175], v154 offset:1024
	ds_read_b128 v[176:179], v154 offset:2048
	ds_read_b128 v[180:183], v154 offset:3072
	s_add_u32 s26, s24, 0xfff50080
	s_addc_u32 s27, s25, -1
	s_cmp_eq_u32 s53, 40
	s_cselect_b32 s29, s5, s27
	s_cselect_b32 s28, s4, s26
	s_cselect_b32 s27, s23, s52
	s_cselect_b32 s26, s22, s51
	v_lshl_add_u64 v[150:151], s[24:25], 0, v[138:139]
	s_add_i32 m0, s33, 0xc000
	ds_read_b128 v[184:187], v155
	ds_read_b128 v[188:191], v155 offset:1024
	ds_read_b128 v[192:195], v155 offset:2048
	ds_read_b128 v[196:199], v155 offset:3072
	ds_read_b128 v[200:203], v155 offset:4096
	ds_read_b128 v[204:207], v155 offset:5120
	ds_read_b128 v[208:211], v155 offset:6144
	ds_read_b128 v[212:215], v155 offset:7168
	global_load_lds_dwordx4 v[150:151], off
	v_lshl_add_u64 v[150:151], s[24:25], 0, v[140:141]
	s_add_i32 m0, s33, 0xe000
	s_nop 0
	global_load_lds_dwordx4 v[150:151], off
	s_waitcnt vmcnt(8)
	s_bitcmp1_b32 s12, 0
	s_cbranch_scc1 .Lnlt_861_4
	s_waitcnt lgkmcnt(0)
.Lnlt_861_4:
	s_barrier
	s_waitcnt lgkmcnt(0)
	v_mfma_f32_16x16x32_bf16 v[124:127], v[146:149], v[184:187], v[124:127]
	v_mfma_f32_16x16x32_bf16 v[120:123], v[160:163], v[184:187], v[120:123]
	v_mfma_f32_16x16x32_bf16 v[108:111], v[146:149], v[192:195], v[108:111]
	v_mfma_f32_16x16x32_bf16 v[104:107], v[160:163], v[192:195], v[104:107]
	v_mfma_f32_16x16x32_bf16 v[92:95], v[146:149], v[200:203], v[92:95]
	v_mfma_f32_16x16x32_bf16 v[88:91], v[160:163], v[200:203], v[88:91]
	v_mfma_f32_16x16x32_bf16 v[76:79], v[146:149], v[208:211], v[76:79]
	v_mfma_f32_16x16x32_bf16 v[72:75], v[160:163], v[208:211], v[72:75]
	v_mfma_f32_16x16x32_bf16 v[124:127], v[156:159], v[188:191], v[124:127]
	v_mfma_f32_16x16x32_bf16 v[120:123], v[164:167], v[188:191], v[120:123]
	v_mfma_f32_16x16x32_bf16 v[108:111], v[156:159], v[196:199], v[108:111]
	v_mfma_f32_16x16x32_bf16 v[104:107], v[164:167], v[196:199], v[104:107]
	v_mfma_f32_16x16x32_bf16 v[92:95], v[156:159], v[204:207], v[92:95]
	v_mfma_f32_16x16x32_bf16 v[88:91], v[164:167], v[204:207], v[88:91]
	v_mfma_f32_16x16x32_bf16 v[76:79], v[156:159], v[212:215], v[76:79]
	v_mfma_f32_16x16x32_bf16 v[72:75], v[164:167], v[212:215], v[72:75]
	v_mfma_f32_16x16x32_bf16 v[116:119], v[168:171], v[184:187], v[116:119]
	v_mfma_f32_16x16x32_bf16 v[112:115], v[176:179], v[184:187], v[112:115]
	v_mfma_f32_16x16x32_bf16 v[100:103], v[168:171], v[192:195], v[100:103]
	v_mfma_f32_16x16x32_bf16 v[96:99], v[176:179], v[192:195], v[96:99]
	v_mfma_f32_16x16x32_bf16 v[84:87], v[168:171], v[200:203], v[84:87]
	v_mfma_f32_16x16x32_bf16 v[80:83], v[176:179], v[200:203], v[80:83]
	v_mfma_f32_16x16x32_bf16 v[68:71], v[168:171], v[208:211], v[68:71]
	v_mfma_f32_16x16x32_bf16 v[64:67], v[176:179], v[208:211], v[64:67]
	v_mfma_f32_16x16x32_bf16 v[116:119], v[172:175], v[188:191], v[116:119]
	v_mfma_f32_16x16x32_bf16 v[112:115], v[180:183], v[188:191], v[112:115]
	v_mfma_f32_16x16x32_bf16 v[100:103], v[172:175], v[196:199], v[100:103]
	v_mfma_f32_16x16x32_bf16 v[96:99], v[180:183], v[196:199], v[96:99]
	v_mfma_f32_16x16x32_bf16 v[84:87], v[172:175], v[204:207], v[84:87]
	v_mfma_f32_16x16x32_bf16 v[80:83], v[180:183], v[204:207], v[80:83]
	v_mfma_f32_16x16x32_bf16 v[68:71], v[172:175], v[212:215], v[68:71]
	v_mfma_f32_16x16x32_bf16 v[64:67], v[180:183], v[212:215], v[64:67]
	s_barrier
	s_add_i32 s56, s45, s31
	s_mov_b32 m0, s56
	ds_read_b128 v[184:187], v155 offset:16384
	ds_read_b128 v[188:191], v155 offset:17408
	ds_read_b128 v[192:195], v155 offset:18432
	ds_read_b128 v[196:199], v155 offset:19456
	ds_read_b128 v[200:203], v155 offset:20480
	ds_read_b128 v[204:207], v155 offset:21504
	ds_read_b128 v[208:211], v155 offset:22528
	ds_read_b128 v[212:215], v155 offset:23552
	s_add_i32 m0, s56, 0x2000
	s_add_u32 s56, s26, 0xb0000
	v_lshl_add_u64 v[216:217], s[26:27], 0, v[134:135]
	s_addc_u32 s57, s27, 0
	s_add_i32 s58, s46, s31
	s_mov_b32 m0, s58
	v_lshl_add_u64 v[220:221], s[28:29], 0, v[132:133]
	s_add_i32 m0, s58, 0x2000
	s_nop 0
	v_lshl_add_u64 v[218:219], s[28:29], 0, v[128:129]
	s_mov_b32 m0, s33
	s_nop 0
	s_mov_b32 m0, s36
	s_nop 0
	s_waitcnt vmcnt(2)
	s_bitcmp1_b32 s12, 0
	s_cbranch_scc1 .Lnlt_861_5
	s_waitcnt lgkmcnt(0)
; #define PG8_STAGE(bufoff, gbase, voff) do { _Pragma("unroll") for (int _i = 0; _i < 2; ++_i) \
;         __builtin_amdgcn_global_load_lds((const unsigned*)((const char*)(gbase) + (voff)[_i]), (PG8_LAS unsigned*)(lds + (bufoff) + ldsw + _i * 8192), 16, 0, 0); } while (0)
; #define PG8_LDA(dst, b, h) do { _Pragma("unroll") for (int m = 0; m < 4; ++m) _Pragma("unroll") for (int k = 0; k < 2; ++k) dst[m][k] = *(const PG8_LAS bf16x8*)(lds + PG8_SA(b, h) + aoff + m * 2048 + k * 1024); } while (0)
; #define PG8_LDB(dst, b, h) do { _Pragma("unroll") for (int n = 0; n < 2; ++n) _Pragma("unroll") for (int k = 0; k < 2; ++k) dst[n][k] = *(const PG8_LAS bf16x8*)(lds + PG8_SB(b, h) + boff + n * 2048 + k * 1024); } while (0)
; #define PG8_MMA(ai, bj, At, Bt) do { __builtin_amdgcn_s_setprio(1); _Pragma("unroll") for (int m = 0; m < 4; ++m) _Pragma("unroll") for (int n = 0; n < 2; ++n) _Pragma("unroll") for (int k = 0; k < 2; ++k) \
;         acc[ai][bj][m][n] = __builtin_amdgcn_mfma_f32_16x16x32_bf16(Bt[n][k], At[m][k], acc[ai][bj][m][n], 0, 0, 0); __builtin_amdgcn_s_setprio(0); } while (0)
; #define PG8_WAIT_V(n) asm volatile("s_waitcnt vmcnt(" #n ")" ::: "memory")
; #define PG8_WAIT_L(n) asm volatile("s_waitcnt lgkmcnt(" #n ")" ::: "memory")
; #define PG8_BAR __builtin_amdgcn_s_barrier()
; #define PG8_SCHED __builtin_amdgcn_sched_barrier(0)
; template <class Epi, class Sched, bool ALIGN_EPI = false, bool SP2 = false>
; __device__ __forceinline__ void gemm_phase(PG8_LAS unsigned char* lds, const Gemm g, const Sched& S, const Epi& E) {
;     ...
;             PG8_WAIT_V(8); PG8_WAIT_L(0); PG8_BAR; PG8_MMA(1, 0, At, B0); PG8_MMA(1, 1, At, B1); PG8_BAR; PG8_SCHED;
;             PG8_LDB(B0, 1, 0); PG8_LDB(B1, 1, 1); PG8_SCHED; PG8_LDA(At, 1, 0); PG8_STAGE(PG8_SA(0, 1), a2 + hstep, voffA);
;             PG8_WAIT_V(8); PG8_WAIT_L(0); PG8_BAR; PG8_MMA(0, 0, At, B0); PG8_MMA(0, 1, At, B1); PG8_BAR; PG8_SCHED;
.Lnlt_861_5:
	s_barrier
	s_waitcnt lgkmcnt(0)
	v_mfma_f32_16x16x32_bf16 v[60:63], v[146:149], v[184:187], v[60:63]
	v_mfma_f32_16x16x32_bf16 v[56:59], v[160:163], v[184:187], v[56:59]
	v_mfma_f32_16x16x32_bf16 v[44:47], v[146:149], v[192:195], v[44:47]
	v_mfma_f32_16x16x32_bf16 v[40:43], v[160:163], v[192:195], v[40:43]
	v_mfma_f32_16x16x32_bf16 v[28:31], v[146:149], v[200:203], v[28:31]
	v_mfma_f32_16x16x32_bf16 v[24:27], v[160:163], v[200:203], v[24:27]
	v_mfma_f32_16x16x32_bf16 v[12:15], v[146:149], v[208:211], v[12:15]
	v_mfma_f32_16x16x32_bf16 v[8:11], v[160:163], v[208:211], v[8:11]
	v_mfma_f32_16x16x32_bf16 v[60:63], v[156:159], v[188:191], v[60:63]
	v_mfma_f32_16x16x32_bf16 v[56:59], v[164:167], v[188:191], v[56:59]
	v_mfma_f32_16x16x32_bf16 v[44:47], v[156:159], v[196:199], v[44:47]
	v_mfma_f32_16x16x32_bf16 v[40:43], v[164:167], v[196:199], v[40:43]
	v_mfma_f32_16x16x32_bf16 v[28:31], v[156:159], v[204:207], v[28:31]
	v_mfma_f32_16x16x32_bf16 v[24:27], v[164:167], v[204:207], v[24:27]
	v_mfma_f32_16x16x32_bf16 v[12:15], v[156:159], v[212:215], v[12:15]
	v_mfma_f32_16x16x32_bf16 v[8:11], v[164:167], v[212:215], v[8:11]
	v_mfma_f32_16x16x32_bf16 v[52:55], v[168:171], v[184:187], v[52:55]
	v_mfma_f32_16x16x32_bf16 v[48:51], v[176:179], v[184:187], v[48:51]
	v_mfma_f32_16x16x32_bf16 v[36:39], v[168:171], v[192:195], v[36:39]
	v_mfma_f32_16x16x32_bf16 v[32:35], v[176:179], v[192:195], v[32:35]
	v_mfma_f32_16x16x32_bf16 v[20:23], v[168:171], v[200:203], v[20:23]
	v_mfma_f32_16x16x32_bf16 v[16:19], v[176:179], v[200:203], v[16:19]
	v_mfma_f32_16x16x32_bf16 v[4:7], v[168:171], v[208:211], v[4:7]
	v_mfma_f32_16x16x32_bf16 v[0:3], v[176:179], v[208:211], v[0:3]
	v_mfma_f32_16x16x32_bf16 v[52:55], v[172:175], v[188:191], v[52:55]
	v_mfma_f32_16x16x32_bf16 v[48:51], v[180:183], v[188:191], v[48:51]
	v_mfma_f32_16x16x32_bf16 v[36:39], v[172:175], v[196:199], v[36:39]
	v_mfma_f32_16x16x32_bf16 v[32:35], v[180:183], v[196:199], v[32:35]
	v_mfma_f32_16x16x32_bf16 v[20:23], v[172:175], v[204:207], v[20:23]
	v_mfma_f32_16x16x32_bf16 v[16:19], v[180:183], v[204:207], v[16:19]
	v_mfma_f32_16x16x32_bf16 v[4:7], v[172:175], v[212:215], v[4:7]
	v_mfma_f32_16x16x32_bf16 v[0:3], v[180:183], v[212:215], v[0:3]
	s_barrier
	s_add_i32 s56, 0, 0x18000
	s_add_i32 s57, 0, 0x1c000
	v_add_u32_e32 v164, s56, v152
	v_add_u32_e32 v180, s57, v152
	ds_read_b128 v[146:149], v164
	ds_read_b128 v[156:159], v164 offset:1024
	ds_read_b128 v[160:163], v164 offset:2048
	ds_read_b128 v[164:167], v164 offset:3072
	ds_read_b128 v[168:171], v180
	ds_read_b128 v[172:175], v180 offset:1024
	ds_read_b128 v[176:179], v180 offset:2048
	ds_read_b128 v[180:183], v180 offset:3072
	s_add_u32 s28, s28, 0xb0000
	s_addc_u32 s29, s29, 0
	s_mov_b32 m0, s37
	ds_read_b128 v[184:187], v155 offset:32768
	ds_read_b128 v[188:191], v155 offset:33792
	ds_read_b128 v[192:195], v155 offset:34816
	ds_read_b128 v[196:199], v155 offset:35840
	ds_read_b128 v[200:203], v155 offset:36864
	ds_read_b128 v[204:207], v155 offset:37888
	ds_read_b128 v[208:211], v155 offset:38912
	ds_read_b128 v[212:215], v155 offset:39936
	s_mov_b32 m0, s38
	s_nop 0
	s_waitcnt vmcnt(0)
	s_bitcmp1_b32 s12, 0
	s_cbranch_scc1 .Lnlt_861_6
	s_waitcnt lgkmcnt(0)
; #define PG8_STAGE(bufoff, gbase, voff) do { _Pragma("unroll") for (int _i = 0; _i < 2; ++_i) \
;         __builtin_amdgcn_global_load_lds((const unsigned*)((const char*)(gbase) + (voff)[_i]), (PG8_LAS unsigned*)(lds + (bufoff) + ldsw + _i * 8192), 16, 0, 0); } while (0)
; #define PG8_LDA(dst, b, h) do { _Pragma("unroll") for (int m = 0; m < 4; ++m) _Pragma("unroll") for (int k = 0; k < 2; ++k) dst[m][k] = *(const PG8_LAS bf16x8*)(lds + PG8_SA(b, h) + aoff + m * 2048 + k * 1024); } while (0)
; #define PG8_MMA(ai, bj, At, Bt) do { __builtin_amdgcn_s_setprio(1); _Pragma("unroll") for (int m = 0; m < 4; ++m) _Pragma("unroll") for (int n = 0; n < 2; ++n) _Pragma("unroll") for (int k = 0; k < 2; ++k) \
;         acc[ai][bj][m][n] = __builtin_amdgcn_mfma_f32_16x16x32_bf16(Bt[n][k], At[m][k], acc[ai][bj][m][n], 0, 0, 0); __builtin_amdgcn_s_setprio(0); } while (0)
; #define PG8_WAIT_V(n) asm volatile("s_waitcnt vmcnt(" #n ")" ::: "memory")
; #define PG8_WAIT_L(n) asm volatile("s_waitcnt lgkmcnt(" #n ")" ::: "memory")
; #define PG8_BAR __builtin_amdgcn_s_barrier()
; #define PG8_SCHED __builtin_amdgcn_sched_barrier(0)
; template <class Epi, class Sched, bool ALIGN_EPI = false, bool SP2 = false>
; __device__ __forceinline__ void gemm_phase(PG8_LAS unsigned char* lds, const Gemm g, const Sched& S, const Epi& E) {
;     ...
;             PG8_WAIT_V(8); PG8_WAIT_L(0); PG8_BAR; PG8_MMA(0, 0, At, B0); PG8_MMA(0, 1, At, B1); PG8_BAR; PG8_SCHED;
;             PG8_LDA(At, 1, 1); PG8_STAGE(PG8_SB(1, 0), b3, voffB); PG8_STAGE(PG8_SB(1, 1), b3 + hstep, voffB); PG8_STAGE(PG8_SA(1, 0), a3, voffA);
;             PG8_WAIT_V(8); PG8_WAIT_L(0); PG8_BAR; PG8_MMA(1, 0, At, B0); PG8_MMA(1, 1, At, B1); PG8_BAR; PG8_SCHED;
;     ...
;         if constexpr (ALIGN_EPI) { if (wr == 0) PG8_BAR; }
.Lnlt_861_6:
	s_barrier
	s_waitcnt lgkmcnt(0)
	v_mfma_f32_16x16x32_bf16 v[124:127], v[146:149], v[184:187], v[124:127]
	v_mfma_f32_16x16x32_bf16 v[120:123], v[160:163], v[184:187], v[120:123]
	v_mfma_f32_16x16x32_bf16 v[108:111], v[146:149], v[192:195], v[108:111]
	v_mfma_f32_16x16x32_bf16 v[104:107], v[160:163], v[192:195], v[104:107]
	v_mfma_f32_16x16x32_bf16 v[92:95], v[146:149], v[200:203], v[92:95]
	v_mfma_f32_16x16x32_bf16 v[88:91], v[160:163], v[200:203], v[88:91]
	v_mfma_f32_16x16x32_bf16 v[76:79], v[146:149], v[208:211], v[76:79]
	v_mfma_f32_16x16x32_bf16 v[72:75], v[160:163], v[208:211], v[72:75]
	v_mfma_f32_16x16x32_bf16 v[124:127], v[156:159], v[188:191], v[124:127]
	v_mfma_f32_16x16x32_bf16 v[120:123], v[164:167], v[188:191], v[120:123]
	v_mfma_f32_16x16x32_bf16 v[108:111], v[156:159], v[196:199], v[108:111]
	v_mfma_f32_16x16x32_bf16 v[104:107], v[164:167], v[196:199], v[104:107]
	v_mfma_f32_16x16x32_bf16 v[92:95], v[156:159], v[204:207], v[92:95]
	v_mfma_f32_16x16x32_bf16 v[88:91], v[164:167], v[204:207], v[88:91]
	v_mfma_f32_16x16x32_bf16 v[76:79], v[156:159], v[212:215], v[76:79]
	v_mfma_f32_16x16x32_bf16 v[72:75], v[164:167], v[212:215], v[72:75]
	v_mfma_f32_16x16x32_bf16 v[116:119], v[168:171], v[184:187], v[116:119]
	v_mfma_f32_16x16x32_bf16 v[112:115], v[176:179], v[184:187], v[112:115]
	v_mfma_f32_16x16x32_bf16 v[100:103], v[168:171], v[192:195], v[100:103]
	v_mfma_f32_16x16x32_bf16 v[96:99], v[176:179], v[192:195], v[96:99]
	v_mfma_f32_16x16x32_bf16 v[84:87], v[168:171], v[200:203], v[84:87]
	v_mfma_f32_16x16x32_bf16 v[80:83], v[176:179], v[200:203], v[80:83]
	v_mfma_f32_16x16x32_bf16 v[68:71], v[168:171], v[208:211], v[68:71]
	v_mfma_f32_16x16x32_bf16 v[64:67], v[176:179], v[208:211], v[64:67]
	v_mfma_f32_16x16x32_bf16 v[116:119], v[172:175], v[188:191], v[116:119]
	v_mfma_f32_16x16x32_bf16 v[112:115], v[180:183], v[188:191], v[112:115]
	v_mfma_f32_16x16x32_bf16 v[100:103], v[172:175], v[196:199], v[100:103]
	v_mfma_f32_16x16x32_bf16 v[96:99], v[180:183], v[196:199], v[96:99]
	v_mfma_f32_16x16x32_bf16 v[84:87], v[172:175], v[204:207], v[84:87]
	v_mfma_f32_16x16x32_bf16 v[80:83], v[180:183], v[204:207], v[80:83]
	v_mfma_f32_16x16x32_bf16 v[68:71], v[172:175], v[212:215], v[68:71]
	v_mfma_f32_16x16x32_bf16 v[64:67], v[180:183], v[212:215], v[64:67]
	s_barrier
	s_add_i32 s28, s56, s31
	s_mov_b32 m0, s28
	ds_read_b128 v[184:187], v155 offset:49152
	ds_read_b128 v[188:191], v155 offset:50176
	ds_read_b128 v[192:195], v155 offset:51200
	ds_read_b128 v[196:199], v155 offset:52224
	ds_read_b128 v[200:203], v155 offset:53248
	ds_read_b128 v[204:207], v155 offset:54272
	ds_read_b128 v[208:211], v155 offset:55296
	ds_read_b128 v[212:215], v155 offset:56320
	s_add_u32 s98, s26, s10
	s_addc_u32 s99, s27, s11
	s_add_i32 m0, s28, 0x2000
	s_add_u32 s26, s26, 0xb0080
	v_lshl_add_u64 v[150:151], v[216:217], 0, s[10:11]
	s_addc_u32 s27, s27, 0
	s_add_i32 s28, s57, s31
	s_mov_b32 m0, s28
	s_nop 0
	s_add_i32 m0, s28, 0x2000
	s_nop 0
	v_lshl_add_u64 v[150:151], v[218:219], 0, s[10:11]
	s_mov_b32 m0, s40
	s_nop 0
	v_lshl_add_u64 v[150:151], v[220:221], 0, s[10:11]
	s_mov_b32 m0, s41
	s_nop 0
	s_bitcmp1_b32 s12, 0
	s_cbranch_scc1 .Lnlt_861_7
	s_waitcnt lgkmcnt(0)
.Lnlt_861_7:
	s_barrier
	s_waitcnt lgkmcnt(0)
	v_mfma_f32_16x16x32_bf16 v[60:63], v[146:149], v[184:187], v[60:63]
	v_mfma_f32_16x16x32_bf16 v[56:59], v[160:163], v[184:187], v[56:59]
	v_mfma_f32_16x16x32_bf16 v[44:47], v[146:149], v[192:195], v[44:47]
	v_mfma_f32_16x16x32_bf16 v[40:43], v[160:163], v[192:195], v[40:43]
	v_mfma_f32_16x16x32_bf16 v[28:31], v[146:149], v[200:203], v[28:31]
	v_mfma_f32_16x16x32_bf16 v[24:27], v[160:163], v[200:203], v[24:27]
	v_mfma_f32_16x16x32_bf16 v[12:15], v[146:149], v[208:211], v[12:15]
	v_mfma_f32_16x16x32_bf16 v[8:11], v[160:163], v[208:211], v[8:11]
	v_mfma_f32_16x16x32_bf16 v[60:63], v[156:159], v[188:191], v[60:63]
	v_mfma_f32_16x16x32_bf16 v[56:59], v[164:167], v[188:191], v[56:59]
	v_mfma_f32_16x16x32_bf16 v[44:47], v[156:159], v[196:199], v[44:47]
	v_mfma_f32_16x16x32_bf16 v[40:43], v[164:167], v[196:199], v[40:43]
	v_mfma_f32_16x16x32_bf16 v[28:31], v[156:159], v[204:207], v[28:31]
	v_mfma_f32_16x16x32_bf16 v[24:27], v[164:167], v[204:207], v[24:27]
	v_mfma_f32_16x16x32_bf16 v[12:15], v[156:159], v[212:215], v[12:15]
	v_mfma_f32_16x16x32_bf16 v[8:11], v[164:167], v[212:215], v[8:11]
	v_mfma_f32_16x16x32_bf16 v[52:55], v[168:171], v[184:187], v[52:55]
	v_mfma_f32_16x16x32_bf16 v[48:51], v[176:179], v[184:187], v[48:51]
	v_mfma_f32_16x16x32_bf16 v[36:39], v[168:171], v[192:195], v[36:39]
	v_mfma_f32_16x16x32_bf16 v[32:35], v[176:179], v[192:195], v[32:35]
	v_mfma_f32_16x16x32_bf16 v[20:23], v[168:171], v[200:203], v[20:23]
	v_mfma_f32_16x16x32_bf16 v[16:19], v[176:179], v[200:203], v[16:19]
	v_mfma_f32_16x16x32_bf16 v[4:7], v[168:171], v[208:211], v[4:7]
	v_mfma_f32_16x16x32_bf16 v[0:3], v[176:179], v[208:211], v[0:3]
	v_mfma_f32_16x16x32_bf16 v[52:55], v[172:175], v[188:191], v[52:55]
	v_mfma_f32_16x16x32_bf16 v[48:51], v[180:183], v[188:191], v[48:51]
	v_mfma_f32_16x16x32_bf16 v[36:39], v[172:175], v[196:199], v[36:39]
	v_mfma_f32_16x16x32_bf16 v[32:35], v[180:183], v[196:199], v[32:35]
	v_mfma_f32_16x16x32_bf16 v[20:23], v[172:175], v[204:207], v[20:23]
	v_mfma_f32_16x16x32_bf16 v[16:19], v[180:183], v[204:207], v[16:19]
	v_mfma_f32_16x16x32_bf16 v[4:7], v[172:175], v[212:215], v[4:7]
	v_mfma_f32_16x16x32_bf16 v[0:3], v[180:183], v[212:215], v[0:3]
	s_add_i32 s53, s53, 2
	s_add_u32 s24, s24, 0x100
	s_addc_u32 s25, s25, 0
	s_add_u32 s51, s51, 0x100
	s_addc_u32 s52, s52, 0
	s_barrier
.Ltl_861_done:
	s_and_b64 vcc, exec, s[12:13]
	s_cbranch_vccz .LBB0_864
	s_barrier
